# residual-epilogue hb stores with sc1 (write-through)
# baseline (speedup 1.0000x reference)
; __device__ __forceinline__ unsigned pk2(float lo, float hi) { const f32x2 v = {lo, hi}; return __builtin_bit_cast(unsigned, __builtin_convertvector(v, hbf2)); }
;     __device__ __forceinline__ void operator()(const f32x4 (&acc)[2][2][4][2], const Unit& u, int wr, int wc, int fr, int fq, LAS f32x4* rsc, bool reuse) const {
;     ...
;                     u32x4 hr[4][2];
; #pragma unroll
;                     for (int m = 0; m < 4; ++m)
; #pragma unroll
;                         for (int bj = 0; bj < 2; ++bj) hr[m][bj] = *(const u32x4*)(hinb + (size_t)(row0 + ai * HALF + m * 16) * DM + u.pn * BM + bj * HALF + cl);
;                     asm volatile("" ::: "memory");
; #pragma unroll
;                     for (int m = 0; m < 4; ++m)
; #pragma unroll
;                         for (int bj = 0; bj < 2; ++bj) { const u32x4 r = hr[m][bj]; hv[m][bj][0] = (f32x4){bflo(r.x), bfhi(r.x), bflo(r.y), bfhi(r.y)}; hv[m][bj][1] = (f32x4){bflo(r.z), bfhi(r.z), bflo(r.w), bfhi(r.w)}; }
;                 }
; #pragma unroll
;                 for (int m = 0; m < 4; ++m) {
;                     const int row = row0 + ai * HALF + m * 16; float ss = 0.f;
; #pragma unroll
;                     for (int bj = 0; bj < 2; ++bj) {
;                         const size_t off = (size_t)row * DM + u.pn * BM + bj * HALF + cl;
;                         const f32x4 o0 = hv[m][bj][0] + acc[ai][bj][m][0] * alpha, o1 = hv[m][bj][1] + acc[ai][bj][m][1] * alpha;
;                         ss += (o0[0] * o0[0] + o0[1] * o0[1]) + (o0[2] * o0[2] + o0[3] * o0[3]) + (o1[0] * o1[0] + o1[1] * o1[1]) + (o1[2] * o1[2] + o1[3] * o1[3]);
;                         if (hb) { u32x4 w; w.x = pk2(o0[0], o0[1]); w.y = pk2(o0[2], o0[3]); w.z = pk2(o1[0], o1[1]); w.w = pk2(o1[2], o1[3]); *(u32x4*)(hb + off) = w; }
.LBB0_415:
	s_lshl_b32 s26, s73, 8
	s_ashr_i32 s27, s26, 31
	s_lshl_b64 s[62:63], s[26:27], 1
	s_add_u32 s48, s48, s62
	s_addc_u32 s49, s3, s63
	v_lshlrev_b32_e32 v2, 1, v204
	v_ashrrev_i32_e32 v211, 31, v210
	v_lshl_add_u64 v[162:163], s[48:49], 0, v[2:3]
	v_lshlrev_b64 v[160:161], 12, v[210:211]
	v_lshl_add_u64 v[132:133], v[162:163], 0, v[160:161]
	flat_load_dwordx4 v[172:175], v[132:133]
	flat_load_dwordx4 v[156:159], v[132:133] offset:256
	v_or_b32_e32 v132, 16, v210
	v_ashrrev_i32_e32 v133, 31, v132
	v_lshlrev_b64 v[168:169], 12, v[132:133]
	v_lshl_add_u64 v[132:133], v[162:163], 0, v[168:169]
	flat_load_dwordx4 v[152:155], v[132:133]
	flat_load_dwordx4 v[148:151], v[132:133] offset:256
	v_or_b32_e32 v132, 32, v210
	v_ashrrev_i32_e32 v133, 31, v132
	v_lshlrev_b64 v[166:167], 12, v[132:133]
	v_lshl_add_u64 v[132:133], v[162:163], 0, v[166:167]
	flat_load_dwordx4 v[144:147], v[132:133]
	flat_load_dwordx4 v[140:143], v[132:133] offset:256
	v_or_b32_e32 v132, 48, v210
	v_ashrrev_i32_e32 v133, 31, v132
	v_lshlrev_b64 v[164:165], 12, v[132:133]
	v_lshl_add_u64 v[132:133], v[162:163], 0, v[164:165]
	flat_load_dwordx4 v[136:139], v[132:133]
	s_nop 0
	flat_load_dwordx4 v[132:135], v[132:133] offset:256
	v_lshl_add_u64 v[160:161], s[24:25], 0, v[160:161]
	s_cmp_lg_u64 s[24:25], 0
	v_lshl_add_u64 v[170:171], s[26:27], 1, v[160:161]
	s_cselect_b64 s[62:63], -1, 0
	s_and_b64 vcc, exec, s[62:63]
	s_waitcnt vmcnt(0) lgkmcnt(0)
	v_lshlrev_b32_e32 v160, 16, v172
	v_and_b32_e32 v161, 0xffff0000, v172
	v_lshlrev_b32_e32 v172, 16, v173
	v_and_b32_e32 v173, 0xffff0000, v173
	v_lshlrev_b32_e32 v178, 16, v174
	v_and_b32_e32 v179, 0xffff0000, v174
	v_lshlrev_b32_e32 v180, 16, v175
	v_and_b32_e32 v181, 0xffff0000, v175
	v_pk_fma_f32 v[174:175], v[130:131], s[50:51], v[172:173] op_sel_hi:[1,0,1]
	v_pk_fma_f32 v[176:177], v[128:129], s[50:51], v[160:161] op_sel_hi:[1,0,1]
	v_pk_fma_f32 v[160:161], v[122:123], s[50:51], v[180:181] op_sel_hi:[1,0,1]
	v_pk_fma_f32 v[172:173], v[120:121], s[50:51], v[178:179] op_sel_hi:[1,0,1]
	s_cbranch_vccz .LBB0_417
	v_cvt_pk_bf16_f32 v178, v176, v177
	v_cvt_pk_bf16_f32 v179, v174, v175
	v_cvt_pk_bf16_f32 v180, v172, v173
	v_cvt_pk_bf16_f32 v181, v160, v161
	v_lshl_add_u64 v[182:183], v[170:171], 0, v[2:3]
	flat_store_dwordx4 v[182:183], v[178:181] sc1
.LBB0_417:
	s_mov_b32 s51, s50
	s_nop 0
	v_lshlrev_b32_e32 v178, 16, v156
	v_and_b32_e32 v179, 0xffff0000, v156
	v_lshlrev_b32_e32 v156, 16, v157
	v_and_b32_e32 v157, 0xffff0000, v157
	v_lshlrev_b32_e32 v180, 16, v158
	v_and_b32_e32 v181, 0xffff0000, v158
	v_lshlrev_b32_e32 v158, 16, v159
	v_and_b32_e32 v159, 0xffff0000, v159
	s_mov_b32 s48, s50
	s_mov_b32 s49, s50
	v_cndmask_b32_e64 v182, 0, 1, s[62:63]
	v_pk_fma_f32 v[156:157], v[126:127], s[48:49], v[156:157]
	v_pk_fma_f32 v[178:179], v[124:125], s[50:51], v[178:179]
	v_pk_fma_f32 v[158:159], v[118:119], s[48:49], v[158:159]
	v_cmp_ne_u32_e64 s[48:49], 1, v182
	s_andn2_b64 vcc, exec, s[62:63]
	v_pk_fma_f32 v[180:181], v[116:117], s[50:51], v[180:181]
	s_cbranch_vccnz .LBB0_419
	v_cvt_pk_bf16_f32 v182, v178, v179
	v_cvt_pk_bf16_f32 v183, v156, v157
	v_cvt_pk_bf16_f32 v184, v180, v181
	v_cvt_pk_bf16_f32 v185, v158, v159
	v_lshl_add_u64 v[170:171], v[170:171], 0, v[2:3]
	flat_store_dwordx4 v[170:171], v[182:185] offset:256 sc1

; __device__ __forceinline__ unsigned pk2(float lo, float hi) { const f32x2 v = {lo, hi}; return __builtin_bit_cast(unsigned, __builtin_convertvector(v, hbf2)); }
;     __device__ __forceinline__ void operator()(const f32x4 (&acc)[2][2][4][2], const Unit& u, int wr, int wc, int fr, int fq, LAS f32x4* rsc, bool reuse) const {
;     ...
;                 for (int m = 0; m < 4; ++m) {
;                     const int row = row0 + ai * HALF + m * 16; float ss = 0.f;
; #pragma unroll
;                     for (int bj = 0; bj < 2; ++bj) {
;                         const size_t off = (size_t)row * DM + u.pn * BM + bj * HALF + cl;
;                         const f32x4 o0 = hv[m][bj][0] + acc[ai][bj][m][0] * alpha, o1 = hv[m][bj][1] + acc[ai][bj][m][1] * alpha;
;                         ss += (o0[0] * o0[0] + o0[1] * o0[1]) + (o0[2] * o0[2] + o0[3] * o0[3]) + (o1[0] * o1[0] + o1[1] * o1[1]) + (o1[2] * o1[2] + o1[3] * o1[3]);
;                         if (hb) { u32x4 w; w.x = pk2(o0[0], o0[1]); w.y = pk2(o0[2], o0[3]); w.z = pk2(o1[0], o1[1]); w.w = pk2(o1[2], o1[3]); *(u32x4*)(hb + off) = w; }
.LBB0_421:
	s_or_b64 exec, exec, s[28:29]
	v_lshlrev_b32_e32 v156, 16, v152
	s_waitcnt lgkmcnt(0)
	v_and_b32_e32 v157, 0xffff0000, v152
	v_lshlrev_b32_e32 v152, 16, v153
	v_and_b32_e32 v153, 0xffff0000, v153
	v_lshlrev_b32_e32 v158, 16, v154
	v_and_b32_e32 v159, 0xffff0000, v154
	v_lshlrev_b32_e32 v154, 16, v155
	v_and_b32_e32 v155, 0xffff0000, v155
	s_mov_b32 s28, s50
	s_mov_b32 s29, s50
	v_lshl_add_u64 v[168:169], s[24:25], 0, v[168:169]
	v_pk_fma_f32 v[152:153], v[114:115], s[28:29], v[152:153]
	v_pk_fma_f32 v[156:157], v[112:113], s[50:51], v[156:157]
	v_pk_fma_f32 v[154:155], v[106:107], s[28:29], v[154:155]
	v_pk_fma_f32 v[158:159], v[104:105], s[50:51], v[158:159]
	s_and_b64 vcc, exec, s[48:49]
	v_lshl_add_u64 v[168:169], s[26:27], 1, v[168:169]
	s_cbranch_vccnz .LBB0_423
	v_cvt_pk_bf16_f32 v170, v156, v157
	v_cvt_pk_bf16_f32 v171, v152, v153
	v_cvt_pk_bf16_f32 v172, v158, v159
	v_cvt_pk_bf16_f32 v173, v154, v155
	v_lshl_add_u64 v[174:175], v[168:169], 0, v[2:3]
	flat_store_dwordx4 v[174:175], v[170:173] sc1
.LBB0_423:
	s_nop 1
	v_lshlrev_b32_e32 v170, 16, v148
	v_and_b32_e32 v171, 0xffff0000, v148
	v_lshlrev_b32_e32 v148, 16, v149
	v_and_b32_e32 v149, 0xffff0000, v149
	v_lshlrev_b32_e32 v172, 16, v150
	v_and_b32_e32 v173, 0xffff0000, v150
	v_lshlrev_b32_e32 v150, 16, v151
	v_and_b32_e32 v151, 0xffff0000, v151
	v_pk_fma_f32 v[148:149], v[110:111], s[28:29], v[148:149]
	v_pk_fma_f32 v[170:171], v[108:109], s[50:51], v[170:171]
	v_pk_fma_f32 v[150:151], v[102:103], s[28:29], v[150:151]
	s_and_b64 vcc, exec, s[48:49]
	v_pk_fma_f32 v[172:173], v[100:101], s[50:51], v[172:173]
	s_cbranch_vccnz .LBB0_425
	v_cvt_pk_bf16_f32 v174, v170, v171
	v_cvt_pk_bf16_f32 v175, v148, v149
	v_cvt_pk_bf16_f32 v176, v172, v173
	v_cvt_pk_bf16_f32 v177, v150, v151
	v_lshl_add_u64 v[168:169], v[168:169], 0, v[2:3]
	flat_store_dwordx4 v[168:169], v[174:177] offset:256 sc1

; __device__ __forceinline__ unsigned pk2(float lo, float hi) { const f32x2 v = {lo, hi}; return __builtin_bit_cast(unsigned, __builtin_convertvector(v, hbf2)); }
;     __device__ __forceinline__ void operator()(const f32x4 (&acc)[2][2][4][2], const Unit& u, int wr, int wc, int fr, int fq, LAS f32x4* rsc, bool reuse) const {
;     ...
;                 for (int m = 0; m < 4; ++m) {
;                     const int row = row0 + ai * HALF + m * 16; float ss = 0.f;
; #pragma unroll
;                     for (int bj = 0; bj < 2; ++bj) {
;                         const size_t off = (size_t)row * DM + u.pn * BM + bj * HALF + cl;
;                         const f32x4 o0 = hv[m][bj][0] + acc[ai][bj][m][0] * alpha, o1 = hv[m][bj][1] + acc[ai][bj][m][1] * alpha;
;                         ss += (o0[0] * o0[0] + o0[1] * o0[1]) + (o0[2] * o0[2] + o0[3] * o0[3]) + (o1[0] * o1[0] + o1[1] * o1[1]) + (o1[2] * o1[2] + o1[3] * o1[3]);
;                         if (hb) { u32x4 w; w.x = pk2(o0[0], o0[1]); w.y = pk2(o0[2], o0[3]); w.z = pk2(o1[0], o1[1]); w.w = pk2(o1[2], o1[3]); *(u32x4*)(hb + off) = w; }
.LBB0_427:
	s_or_b64 exec, exec, s[28:29]
	v_lshlrev_b32_e32 v148, 16, v144
	s_waitcnt lgkmcnt(0)
	v_and_b32_e32 v149, 0xffff0000, v144
	v_lshlrev_b32_e32 v144, 16, v145
	v_and_b32_e32 v145, 0xffff0000, v145
	v_lshlrev_b32_e32 v150, 16, v146
	v_and_b32_e32 v151, 0xffff0000, v146
	v_lshlrev_b32_e32 v146, 16, v147
	v_and_b32_e32 v147, 0xffff0000, v147
	s_mov_b32 s28, s50
	s_mov_b32 s29, s50
	v_lshl_add_u64 v[152:153], s[24:25], 0, v[166:167]
	v_pk_fma_f32 v[144:145], v[98:99], s[28:29], v[144:145]
	v_pk_fma_f32 v[148:149], v[96:97], s[50:51], v[148:149]
	v_pk_fma_f32 v[146:147], v[90:91], s[28:29], v[146:147]
	v_pk_fma_f32 v[150:151], v[88:89], s[50:51], v[150:151]
	s_and_b64 vcc, exec, s[48:49]
	v_lshl_add_u64 v[152:153], s[26:27], 1, v[152:153]
	s_cbranch_vccnz .LBB0_429
	v_cvt_pk_bf16_f32 v154, v148, v149
	v_cvt_pk_bf16_f32 v155, v144, v145
	v_cvt_pk_bf16_f32 v156, v150, v151
	v_cvt_pk_bf16_f32 v157, v146, v147
	v_lshl_add_u64 v[158:159], v[152:153], 0, v[2:3]
	flat_store_dwordx4 v[158:159], v[154:157] sc1
.LBB0_429:
	s_nop 1
	v_lshlrev_b32_e32 v154, 16, v140
	v_and_b32_e32 v155, 0xffff0000, v140
	v_lshlrev_b32_e32 v140, 16, v141
	v_and_b32_e32 v141, 0xffff0000, v141
	v_lshlrev_b32_e32 v156, 16, v142
	v_and_b32_e32 v157, 0xffff0000, v142
	v_lshlrev_b32_e32 v142, 16, v143
	v_and_b32_e32 v143, 0xffff0000, v143
	v_pk_fma_f32 v[140:141], v[94:95], s[28:29], v[140:141]
	v_pk_fma_f32 v[154:155], v[92:93], s[50:51], v[154:155]
	v_pk_fma_f32 v[142:143], v[86:87], s[28:29], v[142:143]
	s_and_b64 vcc, exec, s[48:49]
	v_pk_fma_f32 v[156:157], v[84:85], s[50:51], v[156:157]
	s_cbranch_vccnz .LBB0_431
	v_cvt_pk_bf16_f32 v166, v154, v155
	v_cvt_pk_bf16_f32 v167, v140, v141
	v_cvt_pk_bf16_f32 v168, v156, v157
	v_cvt_pk_bf16_f32 v169, v142, v143
	v_lshl_add_u64 v[152:153], v[152:153], 0, v[2:3]
	flat_store_dwordx4 v[152:153], v[166:169] offset:256 sc1

; __device__ __forceinline__ unsigned pk2(float lo, float hi) { const f32x2 v = {lo, hi}; return __builtin_bit_cast(unsigned, __builtin_convertvector(v, hbf2)); }
;     __device__ __forceinline__ void operator()(const f32x4 (&acc)[2][2][4][2], const Unit& u, int wr, int wc, int fr, int fq, LAS f32x4* rsc, bool reuse) const {
;     ...
;                 for (int m = 0; m < 4; ++m) {
;                     const int row = row0 + ai * HALF + m * 16; float ss = 0.f;
; #pragma unroll
;                     for (int bj = 0; bj < 2; ++bj) {
;                         const size_t off = (size_t)row * DM + u.pn * BM + bj * HALF + cl;
;                         const f32x4 o0 = hv[m][bj][0] + acc[ai][bj][m][0] * alpha, o1 = hv[m][bj][1] + acc[ai][bj][m][1] * alpha;
;                         ss += (o0[0] * o0[0] + o0[1] * o0[1]) + (o0[2] * o0[2] + o0[3] * o0[3]) + (o1[0] * o1[0] + o1[1] * o1[1]) + (o1[2] * o1[2] + o1[3] * o1[3]);
;                         if (hb) { u32x4 w; w.x = pk2(o0[0], o0[1]); w.y = pk2(o0[2], o0[3]); w.z = pk2(o1[0], o1[1]); w.w = pk2(o1[2], o1[3]); *(u32x4*)(hb + off) = w; }
.LBB0_433:
	s_or_b64 exec, exec, s[28:29]
	v_lshlrev_b32_e32 v140, 16, v136
	s_waitcnt lgkmcnt(0)
	v_and_b32_e32 v141, 0xffff0000, v136
	v_lshlrev_b32_e32 v136, 16, v137
	v_and_b32_e32 v137, 0xffff0000, v137
	v_lshlrev_b32_e32 v142, 16, v138
	v_and_b32_e32 v143, 0xffff0000, v138
	v_lshlrev_b32_e32 v138, 16, v139
	v_and_b32_e32 v139, 0xffff0000, v139
	s_mov_b32 s28, s50
	s_mov_b32 s29, s50
	v_lshl_add_u64 v[144:145], s[24:25], 0, v[164:165]
	v_pk_fma_f32 v[136:137], v[82:83], s[28:29], v[136:137]
	v_pk_fma_f32 v[140:141], v[80:81], s[50:51], v[140:141]
	v_pk_fma_f32 v[138:139], v[74:75], s[28:29], v[138:139]
	v_pk_fma_f32 v[142:143], v[72:73], s[50:51], v[142:143]
	s_and_b64 vcc, exec, s[48:49]
	v_lshl_add_u64 v[144:145], s[26:27], 1, v[144:145]
	s_cbranch_vccnz .LBB0_435
	v_cvt_pk_bf16_f32 v146, v140, v141
	v_cvt_pk_bf16_f32 v147, v136, v137
	v_cvt_pk_bf16_f32 v148, v142, v143
	v_cvt_pk_bf16_f32 v149, v138, v139
	v_lshl_add_u64 v[150:151], v[144:145], 0, v[2:3]
	flat_store_dwordx4 v[150:151], v[146:149] sc1
.LBB0_435:
	s_nop 1
	v_lshlrev_b32_e32 v146, 16, v132
	v_and_b32_e32 v147, 0xffff0000, v132
	v_lshlrev_b32_e32 v132, 16, v133
	v_and_b32_e32 v133, 0xffff0000, v133
	v_lshlrev_b32_e32 v148, 16, v134
	v_and_b32_e32 v149, 0xffff0000, v134
	v_lshlrev_b32_e32 v134, 16, v135
	v_and_b32_e32 v135, 0xffff0000, v135
	v_pk_fma_f32 v[132:133], v[78:79], s[28:29], v[132:133]
	v_pk_fma_f32 v[146:147], v[76:77], s[50:51], v[146:147]
	v_pk_fma_f32 v[134:135], v[70:71], s[28:29], v[134:135]
	s_and_b64 vcc, exec, s[48:49]
	v_pk_fma_f32 v[148:149], v[68:69], s[50:51], v[148:149]
	s_cbranch_vccnz .LBB0_437
	v_cvt_pk_bf16_f32 v150, v146, v147
	v_cvt_pk_bf16_f32 v151, v132, v133
	v_cvt_pk_bf16_f32 v152, v148, v149
	v_cvt_pk_bf16_f32 v153, v134, v135
	v_lshl_add_u64 v[144:145], v[144:145], 0, v[2:3]
	flat_store_dwordx4 v[144:145], v[150:153] offset:256 sc1

; __device__ __forceinline__ unsigned pk2(float lo, float hi) { const f32x2 v = {lo, hi}; return __builtin_bit_cast(unsigned, __builtin_convertvector(v, hbf2)); }
;     __device__ __forceinline__ void operator()(const f32x4 (&acc)[2][2][4][2], const Unit& u, int wr, int wc, int fr, int fq, LAS f32x4* rsc, bool reuse) const {
;     ...
;                     u32x4 hr[4][2];
; #pragma unroll
;                     for (int m = 0; m < 4; ++m)
; #pragma unroll
;                         for (int bj = 0; bj < 2; ++bj) hr[m][bj] = *(const u32x4*)(hinb + (size_t)(row0 + ai * HALF + m * 16) * DM + u.pn * BM + bj * HALF + cl);
;                     asm volatile("" ::: "memory");
; #pragma unroll
;                     for (int m = 0; m < 4; ++m)
; #pragma unroll
;                         for (int bj = 0; bj < 2; ++bj) { const u32x4 r = hr[m][bj]; hv[m][bj][0] = (f32x4){bflo(r.x), bfhi(r.x), bflo(r.y), bfhi(r.y)}; hv[m][bj][1] = (f32x4){bflo(r.z), bfhi(r.z), bflo(r.w), bfhi(r.w)}; }
;                 }
; #pragma unroll
;                 for (int m = 0; m < 4; ++m) {
;                     const int row = row0 + ai * HALF + m * 16; float ss = 0.f;
; #pragma unroll
;                     for (int bj = 0; bj < 2; ++bj) {
;                         const size_t off = (size_t)row * DM + u.pn * BM + bj * HALF + cl;
;                         const f32x4 o0 = hv[m][bj][0] + acc[ai][bj][m][0] * alpha, o1 = hv[m][bj][1] + acc[ai][bj][m][1] * alpha;
;                         ss += (o0[0] * o0[0] + o0[1] * o0[1]) + (o0[2] * o0[2] + o0[3] * o0[3]) + (o1[0] * o1[0] + o1[1] * o1[1]) + (o1[2] * o1[2] + o1[3] * o1[3]);
;                         if (hb) { u32x4 w; w.x = pk2(o0[0], o0[1]); w.y = pk2(o0[2], o0[3]); w.z = pk2(o1[0], o1[1]); w.w = pk2(o1[2], o1[3]); *(u32x4*)(hb + off) = w; }
.LBB0_439:
	s_or_b64 exec, exec, s[28:29]
	s_waitcnt lgkmcnt(0)
	v_lshlrev_b64 v[132:133], 12, v[210:211]
	s_mov_b64 s[28:29], 0x80000
	v_lshl_add_u64 v[174:175], v[132:133], 0, s[28:29]
	s_mov_b64 s[28:29], 0x90000
	v_lshl_add_u64 v[168:169], v[132:133], 0, s[28:29]
	s_mov_b64 s[28:29], 0xa0000
	v_lshl_add_u64 v[166:167], v[132:133], 0, s[28:29]
	s_mov_b64 s[28:29], 0xb0000
	v_lshl_add_u64 v[134:135], v[162:163], 0, v[174:175]
	v_lshl_add_u64 v[164:165], v[132:133], 0, s[28:29]
	v_lshl_add_u64 v[132:133], v[162:163], 0, v[168:169]
	v_lshl_add_u64 v[136:137], v[162:163], 0, v[166:167]
	flat_load_dwordx4 v[170:173], v[134:135]
	v_lshl_add_u64 v[162:163], v[162:163], 0, v[164:165]
	flat_load_dwordx4 v[156:159], v[134:135] offset:256
	flat_load_dwordx4 v[152:155], v[132:133]
	flat_load_dwordx4 v[148:151], v[132:133] offset:256
	flat_load_dwordx4 v[144:147], v[136:137]
	flat_load_dwordx4 v[140:143], v[136:137] offset:256
	s_nop 0
	flat_load_dwordx4 v[136:139], v[162:163]
	flat_load_dwordx4 v[132:135], v[162:163] offset:256
	s_mov_b32 s28, s50
	s_mov_b32 s29, s50
	v_lshl_add_u64 v[176:177], s[24:25], 0, v[174:175]
	s_and_b64 vcc, exec, s[48:49]
	v_lshl_add_u64 v[176:177], s[26:27], 1, v[176:177]
	s_waitcnt vmcnt(0) lgkmcnt(0)
	v_lshlrev_b32_e32 v162, 16, v170
	v_and_b32_e32 v163, 0xffff0000, v170
	v_lshlrev_b32_e32 v170, 16, v171
	v_and_b32_e32 v171, 0xffff0000, v171
	v_lshlrev_b32_e32 v178, 16, v172
	v_and_b32_e32 v179, 0xffff0000, v172
	v_lshlrev_b32_e32 v180, 16, v173
	v_and_b32_e32 v181, 0xffff0000, v173
	v_pk_fma_f32 v[172:173], v[66:67], s[28:29], v[170:171]
	v_pk_fma_f32 v[174:175], v[64:65], s[50:51], v[162:163]
	v_pk_fma_f32 v[162:163], v[58:59], s[28:29], v[180:181]
	v_pk_fma_f32 v[170:171], v[56:57], s[50:51], v[178:179]
	s_cbranch_vccnz .LBB0_441
	v_cvt_pk_bf16_f32 v178, v174, v175
	v_cvt_pk_bf16_f32 v179, v172, v173
	v_cvt_pk_bf16_f32 v180, v170, v171
	v_cvt_pk_bf16_f32 v181, v162, v163
	v_lshl_add_u64 v[184:185], v[176:177], 0, v[2:3]
	flat_store_dwordx4 v[184:185], v[178:181] sc1
.LBB0_441:
	s_nop 1
	v_lshlrev_b32_e32 v178, 16, v156
	v_and_b32_e32 v179, 0xffff0000, v156
	v_lshlrev_b32_e32 v156, 16, v157
	v_and_b32_e32 v157, 0xffff0000, v157
	v_lshlrev_b32_e32 v180, 16, v158
	v_and_b32_e32 v181, 0xffff0000, v158
	v_lshlrev_b32_e32 v158, 16, v159
	v_and_b32_e32 v159, 0xffff0000, v159
	v_pk_fma_f32 v[156:157], v[62:63], s[28:29], v[156:157]
	v_pk_fma_f32 v[178:179], v[60:61], s[50:51], v[178:179]
	v_pk_fma_f32 v[158:159], v[54:55], s[28:29], v[158:159]
	s_and_b64 vcc, exec, s[48:49]
	v_pk_fma_f32 v[180:181], v[52:53], s[50:51], v[180:181]
	s_cbranch_vccnz .LBB0_443
	v_cvt_pk_bf16_f32 v184, v178, v179
	v_cvt_pk_bf16_f32 v185, v156, v157
	v_cvt_pk_bf16_f32 v186, v180, v181
	v_cvt_pk_bf16_f32 v187, v158, v159
	v_lshl_add_u64 v[176:177], v[176:177], 0, v[2:3]
	flat_store_dwordx4 v[176:177], v[184:187] offset:256 sc1

; __device__ __forceinline__ unsigned pk2(float lo, float hi) { const f32x2 v = {lo, hi}; return __builtin_bit_cast(unsigned, __builtin_convertvector(v, hbf2)); }
;     __device__ __forceinline__ void operator()(const f32x4 (&acc)[2][2][4][2], const Unit& u, int wr, int wc, int fr, int fq, LAS f32x4* rsc, bool reuse) const {
;     ...
;                 for (int m = 0; m < 4; ++m) {
;                     const int row = row0 + ai * HALF + m * 16; float ss = 0.f;
; #pragma unroll
;                     for (int bj = 0; bj < 2; ++bj) {
;                         const size_t off = (size_t)row * DM + u.pn * BM + bj * HALF + cl;
;                         const f32x4 o0 = hv[m][bj][0] + acc[ai][bj][m][0] * alpha, o1 = hv[m][bj][1] + acc[ai][bj][m][1] * alpha;
;                         ss += (o0[0] * o0[0] + o0[1] * o0[1]) + (o0[2] * o0[2] + o0[3] * o0[3]) + (o1[0] * o1[0] + o1[1] * o1[1]) + (o1[2] * o1[2] + o1[3] * o1[3]);
;                         if (hb) { u32x4 w; w.x = pk2(o0[0], o0[1]); w.y = pk2(o0[2], o0[3]); w.z = pk2(o1[0], o1[1]); w.w = pk2(o1[2], o1[3]); *(u32x4*)(hb + off) = w; }
.LBB0_445:
	s_or_b64 exec, exec, s[28:29]
	v_lshlrev_b32_e32 v156, 16, v152
	s_waitcnt lgkmcnt(0)
	v_and_b32_e32 v157, 0xffff0000, v152
	v_lshlrev_b32_e32 v152, 16, v153
	v_and_b32_e32 v153, 0xffff0000, v153
	v_lshlrev_b32_e32 v158, 16, v154
	v_and_b32_e32 v159, 0xffff0000, v154
	v_lshlrev_b32_e32 v154, 16, v155
	v_and_b32_e32 v155, 0xffff0000, v155
	s_mov_b32 s28, s50
	s_mov_b32 s29, s50
	v_lshl_add_u64 v[162:163], s[24:25], 0, v[168:169]
	v_pk_fma_f32 v[152:153], v[50:51], s[28:29], v[152:153]
	v_pk_fma_f32 v[156:157], v[48:49], s[50:51], v[156:157]
	v_pk_fma_f32 v[154:155], v[42:43], s[28:29], v[154:155]
	v_pk_fma_f32 v[158:159], v[40:41], s[50:51], v[158:159]
	s_and_b64 vcc, exec, s[48:49]
	v_lshl_add_u64 v[162:163], s[26:27], 1, v[162:163]
	s_cbranch_vccnz .LBB0_447
	v_cvt_pk_bf16_f32 v168, v156, v157
	v_cvt_pk_bf16_f32 v169, v152, v153
	v_cvt_pk_bf16_f32 v170, v158, v159
	v_cvt_pk_bf16_f32 v171, v154, v155
	v_lshl_add_u64 v[172:173], v[162:163], 0, v[2:3]
	flat_store_dwordx4 v[172:173], v[168:171] sc1
.LBB0_447:
	s_nop 1
	v_lshlrev_b32_e32 v168, 16, v148
	v_and_b32_e32 v169, 0xffff0000, v148
	v_lshlrev_b32_e32 v148, 16, v149
	v_and_b32_e32 v149, 0xffff0000, v149
	v_lshlrev_b32_e32 v170, 16, v150
	v_and_b32_e32 v171, 0xffff0000, v150
	v_lshlrev_b32_e32 v150, 16, v151
	v_and_b32_e32 v151, 0xffff0000, v151
	v_pk_fma_f32 v[148:149], v[46:47], s[28:29], v[148:149]
	v_pk_fma_f32 v[168:169], v[44:45], s[50:51], v[168:169]
	v_pk_fma_f32 v[150:151], v[38:39], s[28:29], v[150:151]
	s_and_b64 vcc, exec, s[48:49]
	v_pk_fma_f32 v[170:171], v[36:37], s[50:51], v[170:171]
	s_cbranch_vccnz .LBB0_449
	v_cvt_pk_bf16_f32 v172, v168, v169
	v_cvt_pk_bf16_f32 v173, v148, v149
	v_cvt_pk_bf16_f32 v174, v170, v171
	v_cvt_pk_bf16_f32 v175, v150, v151
	v_lshl_add_u64 v[162:163], v[162:163], 0, v[2:3]
	flat_store_dwordx4 v[162:163], v[172:175] offset:256 sc1

; __device__ __forceinline__ unsigned pk2(float lo, float hi) { const f32x2 v = {lo, hi}; return __builtin_bit_cast(unsigned, __builtin_convertvector(v, hbf2)); }
;     __device__ __forceinline__ void operator()(const f32x4 (&acc)[2][2][4][2], const Unit& u, int wr, int wc, int fr, int fq, LAS f32x4* rsc, bool reuse) const {
;     ...
;                 for (int m = 0; m < 4; ++m) {
;                     const int row = row0 + ai * HALF + m * 16; float ss = 0.f;
; #pragma unroll
;                     for (int bj = 0; bj < 2; ++bj) {
;                         const size_t off = (size_t)row * DM + u.pn * BM + bj * HALF + cl;
;                         const f32x4 o0 = hv[m][bj][0] + acc[ai][bj][m][0] * alpha, o1 = hv[m][bj][1] + acc[ai][bj][m][1] * alpha;
;                         ss += (o0[0] * o0[0] + o0[1] * o0[1]) + (o0[2] * o0[2] + o0[3] * o0[3]) + (o1[0] * o1[0] + o1[1] * o1[1]) + (o1[2] * o1[2] + o1[3] * o1[3]);
;                         if (hb) { u32x4 w; w.x = pk2(o0[0], o0[1]); w.y = pk2(o0[2], o0[3]); w.z = pk2(o1[0], o1[1]); w.w = pk2(o1[2], o1[3]); *(u32x4*)(hb + off) = w; }
.LBB0_451:
	s_or_b64 exec, exec, s[28:29]
	v_lshlrev_b32_e32 v148, 16, v144
	s_waitcnt lgkmcnt(0)
	v_and_b32_e32 v149, 0xffff0000, v144
	v_lshlrev_b32_e32 v144, 16, v145
	v_and_b32_e32 v145, 0xffff0000, v145
	v_lshlrev_b32_e32 v150, 16, v146
	v_and_b32_e32 v151, 0xffff0000, v146
	v_lshlrev_b32_e32 v146, 16, v147
	v_and_b32_e32 v147, 0xffff0000, v147
	s_mov_b32 s28, s50
	s_mov_b32 s29, s50
	v_lshl_add_u64 v[152:153], s[24:25], 0, v[166:167]
	v_pk_fma_f32 v[144:145], v[34:35], s[28:29], v[144:145]
	v_pk_fma_f32 v[148:149], v[32:33], s[50:51], v[148:149]
	v_pk_fma_f32 v[146:147], v[26:27], s[28:29], v[146:147]
	v_pk_fma_f32 v[150:151], v[24:25], s[50:51], v[150:151]
	s_and_b64 vcc, exec, s[48:49]
	v_lshl_add_u64 v[152:153], s[26:27], 1, v[152:153]
	s_cbranch_vccnz .LBB0_453
	v_cvt_pk_bf16_f32 v154, v148, v149
	v_cvt_pk_bf16_f32 v155, v144, v145
	v_cvt_pk_bf16_f32 v156, v150, v151
	v_cvt_pk_bf16_f32 v157, v146, v147
	v_lshl_add_u64 v[158:159], v[152:153], 0, v[2:3]
	flat_store_dwordx4 v[158:159], v[154:157] sc1
.LBB0_453:
	s_nop 1
	v_lshlrev_b32_e32 v154, 16, v140
	v_and_b32_e32 v155, 0xffff0000, v140
	v_lshlrev_b32_e32 v140, 16, v141
	v_and_b32_e32 v141, 0xffff0000, v141
	v_lshlrev_b32_e32 v156, 16, v142
	v_and_b32_e32 v157, 0xffff0000, v142
	v_lshlrev_b32_e32 v142, 16, v143
	v_and_b32_e32 v143, 0xffff0000, v143
	v_pk_fma_f32 v[140:141], v[30:31], s[28:29], v[140:141]
	v_pk_fma_f32 v[154:155], v[28:29], s[50:51], v[154:155]
	v_pk_fma_f32 v[142:143], v[22:23], s[28:29], v[142:143]
	s_and_b64 vcc, exec, s[48:49]
	v_pk_fma_f32 v[156:157], v[20:21], s[50:51], v[156:157]
	s_cbranch_vccnz .LBB0_455
	v_cvt_pk_bf16_f32 v166, v154, v155
	v_cvt_pk_bf16_f32 v167, v140, v141
	v_cvt_pk_bf16_f32 v168, v156, v157
	v_cvt_pk_bf16_f32 v169, v142, v143
	v_lshl_add_u64 v[152:153], v[152:153], 0, v[2:3]
	flat_store_dwordx4 v[152:153], v[166:169] offset:256 sc1

; __device__ __forceinline__ unsigned pk2(float lo, float hi) { const f32x2 v = {lo, hi}; return __builtin_bit_cast(unsigned, __builtin_convertvector(v, hbf2)); }
;     __device__ __forceinline__ void operator()(const f32x4 (&acc)[2][2][4][2], const Unit& u, int wr, int wc, int fr, int fq, LAS f32x4* rsc, bool reuse) const {
;     ...
;                 for (int m = 0; m < 4; ++m) {
;                     const int row = row0 + ai * HALF + m * 16; float ss = 0.f;
; #pragma unroll
;                     for (int bj = 0; bj < 2; ++bj) {
;                         const size_t off = (size_t)row * DM + u.pn * BM + bj * HALF + cl;
;                         const f32x4 o0 = hv[m][bj][0] + acc[ai][bj][m][0] * alpha, o1 = hv[m][bj][1] + acc[ai][bj][m][1] * alpha;
;                         ss += (o0[0] * o0[0] + o0[1] * o0[1]) + (o0[2] * o0[2] + o0[3] * o0[3]) + (o1[0] * o1[0] + o1[1] * o1[1]) + (o1[2] * o1[2] + o1[3] * o1[3]);
;                         if (hb) { u32x4 w; w.x = pk2(o0[0], o0[1]); w.y = pk2(o0[2], o0[3]); w.z = pk2(o1[0], o1[1]); w.w = pk2(o1[2], o1[3]); *(u32x4*)(hb + off) = w; }
.LBB0_457:
	s_or_b64 exec, exec, s[28:29]
	v_lshlrev_b32_e32 v140, 16, v136
	s_waitcnt lgkmcnt(0)
	v_and_b32_e32 v141, 0xffff0000, v136
	v_lshlrev_b32_e32 v136, 16, v137
	v_and_b32_e32 v137, 0xffff0000, v137
	v_lshlrev_b32_e32 v142, 16, v138
	v_and_b32_e32 v143, 0xffff0000, v138
	v_lshlrev_b32_e32 v138, 16, v139
	v_and_b32_e32 v139, 0xffff0000, v139
	s_mov_b32 s28, s50
	s_mov_b32 s29, s50
	v_lshl_add_u64 v[144:145], s[24:25], 0, v[164:165]
	v_pk_fma_f32 v[136:137], v[18:19], s[28:29], v[136:137]
	v_pk_fma_f32 v[140:141], v[16:17], s[50:51], v[140:141]
	v_pk_fma_f32 v[138:139], v[10:11], s[28:29], v[138:139]
	v_pk_fma_f32 v[142:143], v[8:9], s[50:51], v[142:143]
	s_and_b64 vcc, exec, s[48:49]
	v_lshl_add_u64 v[144:145], s[26:27], 1, v[144:145]
	s_cbranch_vccnz .LBB0_459
	v_cvt_pk_bf16_f32 v146, v140, v141
	v_cvt_pk_bf16_f32 v147, v136, v137
	v_cvt_pk_bf16_f32 v148, v142, v143
	v_cvt_pk_bf16_f32 v149, v138, v139
	v_lshl_add_u64 v[150:151], v[144:145], 0, v[2:3]
	flat_store_dwordx4 v[150:151], v[146:149] sc1
.LBB0_459:
	s_nop 1
	v_lshlrev_b32_e32 v146, 16, v132
	v_and_b32_e32 v147, 0xffff0000, v132
	v_lshlrev_b32_e32 v132, 16, v133
	v_and_b32_e32 v133, 0xffff0000, v133
	v_lshlrev_b32_e32 v148, 16, v134
	v_and_b32_e32 v149, 0xffff0000, v134
	v_lshlrev_b32_e32 v134, 16, v135
	v_and_b32_e32 v135, 0xffff0000, v135
	v_pk_fma_f32 v[132:133], v[14:15], s[28:29], v[132:133]
	v_pk_fma_f32 v[146:147], v[12:13], s[50:51], v[146:147]
	v_pk_fma_f32 v[134:135], v[6:7], s[28:29], v[134:135]
	s_and_b64 vcc, exec, s[48:49]
	v_pk_fma_f32 v[148:149], v[4:5], s[50:51], v[148:149]
	s_cbranch_vccnz .LBB0_461
	v_cvt_pk_bf16_f32 v150, v146, v147
	v_cvt_pk_bf16_f32 v151, v132, v133
	v_cvt_pk_bf16_f32 v152, v148, v149
	v_cvt_pk_bf16_f32 v153, v134, v135
	v_lshl_add_u64 v[144:145], v[144:145], 0, v[2:3]
	flat_store_dwordx4 v[144:145], v[150:153] offset:256 sc1

; __device__ __forceinline__ unsigned pk2(float lo, float hi) { const f32x2 v = {lo, hi}; return __builtin_bit_cast(unsigned, __builtin_convertvector(v, hbf2)); }
;     __device__ __forceinline__ void operator()(const f32x4 (&acc)[2][2][4][2], const Unit& u, int wr, int wc, int fr, int fq, LAS f32x4* rsc, bool reuse) const {
;     ...
;                     u32x4 hr[4][2];
; #pragma unroll
;                     for (int m = 0; m < 4; ++m)
; #pragma unroll
;                         for (int bj = 0; bj < 2; ++bj) hr[m][bj] = *(const u32x4*)(hinb + (size_t)(row0 + ai * HALF + m * 16) * DM + u.pn * BM + bj * HALF + cl);
;                     asm volatile("" ::: "memory");
; #pragma unroll
;                     for (int m = 0; m < 4; ++m)
; #pragma unroll
;                         for (int bj = 0; bj < 2; ++bj) { const u32x4 r = hr[m][bj]; hv[m][bj][0] = (f32x4){bflo(r.x), bfhi(r.x), bflo(r.y), bfhi(r.y)}; hv[m][bj][1] = (f32x4){bflo(r.z), bfhi(r.z), bflo(r.w), bfhi(r.w)}; }
;                 }
; #pragma unroll
;                 for (int m = 0; m < 4; ++m) {
;                     const int row = row0 + ai * HALF + m * 16; float ss = 0.f;
; #pragma unroll
;                     for (int bj = 0; bj < 2; ++bj) {
;                         const size_t off = (size_t)row * DM + u.pn * BM + bj * HALF + cl;
;                         const f32x4 o0 = hv[m][bj][0] + acc[ai][bj][m][0] * alpha, o1 = hv[m][bj][1] + acc[ai][bj][m][1] * alpha;
;                         ss += (o0[0] * o0[0] + o0[1] * o0[1]) + (o0[2] * o0[2] + o0[3] * o0[3]) + (o1[0] * o1[0] + o1[1] * o1[1]) + (o1[2] * o1[2] + o1[3] * o1[3]);
;                         if (hb) { u32x4 w; w.x = pk2(o0[0], o0[1]); w.y = pk2(o0[2], o0[3]); w.z = pk2(o1[0], o1[1]); w.w = pk2(o1[2], o1[3]); *(u32x4*)(hb + off) = w; }
.LBB0_1442:
	s_lshl_b32 s80, s22, 8
	s_ashr_i32 s81, s80, 31
	s_lshl_b64 s[48:49], s[80:81], 1
	s_add_u32 s48, s68, s48
	s_addc_u32 s49, s51, s49
	v_lshlrev_b32_e32 v0, 1, v204
	v_ashrrev_i32_e32 v211, 31, v210
	v_lshl_add_u64 v[160:161], s[48:49], 0, v[0:1]
	v_lshlrev_b64 v[158:159], 12, v[210:211]
	v_lshl_add_u64 v[130:131], v[160:161], 0, v[158:159]
	flat_load_dwordx4 v[170:173], v[130:131]
	flat_load_dwordx4 v[154:157], v[130:131] offset:256
	v_or_b32_e32 v130, 16, v210
	v_ashrrev_i32_e32 v131, 31, v130
	v_lshlrev_b64 v[166:167], 12, v[130:131]
	v_lshl_add_u64 v[130:131], v[160:161], 0, v[166:167]
	flat_load_dwordx4 v[150:153], v[130:131]
	flat_load_dwordx4 v[146:149], v[130:131] offset:256
	v_or_b32_e32 v130, 32, v210
	v_ashrrev_i32_e32 v131, 31, v130
	v_lshlrev_b64 v[164:165], 12, v[130:131]
	v_lshl_add_u64 v[130:131], v[160:161], 0, v[164:165]
	flat_load_dwordx4 v[142:145], v[130:131]
	flat_load_dwordx4 v[138:141], v[130:131] offset:256
	v_or_b32_e32 v130, 48, v210
	v_ashrrev_i32_e32 v131, 31, v130
	v_lshlrev_b64 v[162:163], 12, v[130:131]
	v_lshl_add_u64 v[130:131], v[160:161], 0, v[162:163]
	flat_load_dwordx4 v[134:137], v[130:131]
	s_nop 0
	flat_load_dwordx4 v[130:133], v[130:131] offset:256
	v_lshl_add_u64 v[158:159], s[56:57], 0, v[158:159]
	s_cmp_lg_u64 s[56:57], 0
	v_lshl_add_u64 v[168:169], s[80:81], 1, v[158:159]
	s_cselect_b64 s[68:69], -1, 0
	s_and_b64 vcc, exec, s[68:69]
	s_waitcnt vmcnt(0) lgkmcnt(0)
	v_lshlrev_b32_e32 v158, 16, v170
	v_and_b32_e32 v159, 0xffff0000, v170
	v_lshlrev_b32_e32 v170, 16, v171
	v_and_b32_e32 v171, 0xffff0000, v171
	v_lshlrev_b32_e32 v176, 16, v172
	v_and_b32_e32 v177, 0xffff0000, v172
	v_lshlrev_b32_e32 v178, 16, v173
	v_and_b32_e32 v179, 0xffff0000, v173
	v_pk_fma_f32 v[172:173], v[128:129], s[50:51], v[170:171] op_sel_hi:[1,0,1]
	v_pk_fma_f32 v[174:175], v[126:127], s[50:51], v[158:159] op_sel_hi:[1,0,1]
	v_pk_fma_f32 v[158:159], v[120:121], s[50:51], v[178:179] op_sel_hi:[1,0,1]
	v_pk_fma_f32 v[170:171], v[118:119], s[50:51], v[176:177] op_sel_hi:[1,0,1]
	s_cbranch_vccz .LBB0_1444
	v_cvt_pk_bf16_f32 v176, v174, v175
	v_cvt_pk_bf16_f32 v177, v172, v173
	v_cvt_pk_bf16_f32 v178, v170, v171
	v_cvt_pk_bf16_f32 v179, v158, v159
	v_lshl_add_u64 v[180:181], v[168:169], 0, v[0:1]
	flat_store_dwordx4 v[180:181], v[176:179] sc1
.LBB0_1444:
	s_mov_b32 s51, s50
	s_nop 0
	v_lshlrev_b32_e32 v176, 16, v154
	v_and_b32_e32 v177, 0xffff0000, v154
	v_lshlrev_b32_e32 v154, 16, v155
	v_and_b32_e32 v155, 0xffff0000, v155
	v_lshlrev_b32_e32 v178, 16, v156
	v_and_b32_e32 v179, 0xffff0000, v156
	v_lshlrev_b32_e32 v156, 16, v157
	v_and_b32_e32 v157, 0xffff0000, v157
	s_mov_b32 s48, s50
	s_mov_b32 s49, s50
	v_cndmask_b32_e64 v180, 0, 1, s[68:69]
	v_pk_fma_f32 v[154:155], v[124:125], s[48:49], v[154:155]
	v_pk_fma_f32 v[176:177], v[122:123], s[50:51], v[176:177]
	v_pk_fma_f32 v[156:157], v[116:117], s[48:49], v[156:157]
	v_cmp_ne_u32_e64 s[48:49], 1, v180
	s_andn2_b64 vcc, exec, s[68:69]
	v_pk_fma_f32 v[178:179], v[114:115], s[50:51], v[178:179]
	s_cbranch_vccnz .LBB0_1446
	v_cvt_pk_bf16_f32 v180, v176, v177
	v_cvt_pk_bf16_f32 v181, v154, v155
	v_cvt_pk_bf16_f32 v182, v178, v179
	v_cvt_pk_bf16_f32 v183, v156, v157
	v_lshl_add_u64 v[168:169], v[168:169], 0, v[0:1]
	flat_store_dwordx4 v[168:169], v[180:183] offset:256 sc1

; __device__ __forceinline__ unsigned pk2(float lo, float hi) { const f32x2 v = {lo, hi}; return __builtin_bit_cast(unsigned, __builtin_convertvector(v, hbf2)); }
;     __device__ __forceinline__ void operator()(const f32x4 (&acc)[2][2][4][2], const Unit& u, int wr, int wc, int fr, int fq, LAS f32x4* rsc, bool reuse) const {
;     ...
;                 for (int m = 0; m < 4; ++m) {
;                     const int row = row0 + ai * HALF + m * 16; float ss = 0.f;
; #pragma unroll
;                     for (int bj = 0; bj < 2; ++bj) {
;                         const size_t off = (size_t)row * DM + u.pn * BM + bj * HALF + cl;
;                         const f32x4 o0 = hv[m][bj][0] + acc[ai][bj][m][0] * alpha, o1 = hv[m][bj][1] + acc[ai][bj][m][1] * alpha;
;                         ss += (o0[0] * o0[0] + o0[1] * o0[1]) + (o0[2] * o0[2] + o0[3] * o0[3]) + (o1[0] * o1[0] + o1[1] * o1[1]) + (o1[2] * o1[2] + o1[3] * o1[3]);
;                         if (hb) { u32x4 w; w.x = pk2(o0[0], o0[1]); w.y = pk2(o0[2], o0[3]); w.z = pk2(o1[0], o1[1]); w.w = pk2(o1[2], o1[3]); *(u32x4*)(hb + off) = w; }
.LBB0_1448:
	s_or_b64 exec, exec, s[62:63]
	v_lshlrev_b32_e32 v154, 16, v150
	s_waitcnt lgkmcnt(0)
	v_and_b32_e32 v155, 0xffff0000, v150
	v_lshlrev_b32_e32 v150, 16, v151
	v_and_b32_e32 v151, 0xffff0000, v151
	v_lshlrev_b32_e32 v156, 16, v152
	v_and_b32_e32 v157, 0xffff0000, v152
	v_lshlrev_b32_e32 v152, 16, v153
	v_and_b32_e32 v153, 0xffff0000, v153
	s_mov_b32 s62, s50
	s_mov_b32 s63, s50
	v_lshl_add_u64 v[166:167], s[56:57], 0, v[166:167]
	v_pk_fma_f32 v[150:151], v[112:113], s[62:63], v[150:151]
	v_pk_fma_f32 v[154:155], v[110:111], s[50:51], v[154:155]
	v_pk_fma_f32 v[152:153], v[104:105], s[62:63], v[152:153]
	v_pk_fma_f32 v[156:157], v[102:103], s[50:51], v[156:157]
	s_and_b64 vcc, exec, s[48:49]
	v_lshl_add_u64 v[166:167], s[80:81], 1, v[166:167]
	s_cbranch_vccnz .LBB0_1450
	v_cvt_pk_bf16_f32 v168, v154, v155
	v_cvt_pk_bf16_f32 v169, v150, v151
	v_cvt_pk_bf16_f32 v170, v156, v157
	v_cvt_pk_bf16_f32 v171, v152, v153
	v_lshl_add_u64 v[172:173], v[166:167], 0, v[0:1]
	flat_store_dwordx4 v[172:173], v[168:171] sc1
.LBB0_1450:
	s_nop 1
	v_lshlrev_b32_e32 v168, 16, v146
	v_and_b32_e32 v169, 0xffff0000, v146
	v_lshlrev_b32_e32 v146, 16, v147
	v_and_b32_e32 v147, 0xffff0000, v147
	v_lshlrev_b32_e32 v170, 16, v148
	v_and_b32_e32 v171, 0xffff0000, v148
	v_lshlrev_b32_e32 v148, 16, v149
	v_and_b32_e32 v149, 0xffff0000, v149
	v_pk_fma_f32 v[146:147], v[108:109], s[62:63], v[146:147]
	v_pk_fma_f32 v[168:169], v[106:107], s[50:51], v[168:169]
	v_pk_fma_f32 v[148:149], v[100:101], s[62:63], v[148:149]
	s_and_b64 vcc, exec, s[48:49]
	v_pk_fma_f32 v[170:171], v[98:99], s[50:51], v[170:171]
	s_cbranch_vccnz .LBB0_1452
	v_cvt_pk_bf16_f32 v172, v168, v169
	v_cvt_pk_bf16_f32 v173, v146, v147
	v_cvt_pk_bf16_f32 v174, v170, v171
	v_cvt_pk_bf16_f32 v175, v148, v149
	v_lshl_add_u64 v[166:167], v[166:167], 0, v[0:1]
	flat_store_dwordx4 v[166:167], v[172:175] offset:256 sc1

; __device__ __forceinline__ unsigned pk2(float lo, float hi) { const f32x2 v = {lo, hi}; return __builtin_bit_cast(unsigned, __builtin_convertvector(v, hbf2)); }
;     __device__ __forceinline__ void operator()(const f32x4 (&acc)[2][2][4][2], const Unit& u, int wr, int wc, int fr, int fq, LAS f32x4* rsc, bool reuse) const {
;     ...
;                 for (int m = 0; m < 4; ++m) {
;                     const int row = row0 + ai * HALF + m * 16; float ss = 0.f;
; #pragma unroll
;                     for (int bj = 0; bj < 2; ++bj) {
;                         const size_t off = (size_t)row * DM + u.pn * BM + bj * HALF + cl;
;                         const f32x4 o0 = hv[m][bj][0] + acc[ai][bj][m][0] * alpha, o1 = hv[m][bj][1] + acc[ai][bj][m][1] * alpha;
;                         ss += (o0[0] * o0[0] + o0[1] * o0[1]) + (o0[2] * o0[2] + o0[3] * o0[3]) + (o1[0] * o1[0] + o1[1] * o1[1]) + (o1[2] * o1[2] + o1[3] * o1[3]);
;                         if (hb) { u32x4 w; w.x = pk2(o0[0], o0[1]); w.y = pk2(o0[2], o0[3]); w.z = pk2(o1[0], o1[1]); w.w = pk2(o1[2], o1[3]); *(u32x4*)(hb + off) = w; }
.LBB0_1454:
	s_or_b64 exec, exec, s[62:63]
	v_lshlrev_b32_e32 v146, 16, v142
	s_waitcnt lgkmcnt(0)
	v_and_b32_e32 v147, 0xffff0000, v142
	v_lshlrev_b32_e32 v142, 16, v143
	v_and_b32_e32 v143, 0xffff0000, v143
	v_lshlrev_b32_e32 v148, 16, v144
	v_and_b32_e32 v149, 0xffff0000, v144
	v_lshlrev_b32_e32 v144, 16, v145
	v_and_b32_e32 v145, 0xffff0000, v145
	s_mov_b32 s62, s50
	s_mov_b32 s63, s50
	v_lshl_add_u64 v[150:151], s[56:57], 0, v[164:165]
	v_pk_fma_f32 v[142:143], v[96:97], s[62:63], v[142:143]
	v_pk_fma_f32 v[146:147], v[94:95], s[50:51], v[146:147]
	v_pk_fma_f32 v[144:145], v[88:89], s[62:63], v[144:145]
	v_pk_fma_f32 v[148:149], v[86:87], s[50:51], v[148:149]
	s_and_b64 vcc, exec, s[48:49]
	v_lshl_add_u64 v[150:151], s[80:81], 1, v[150:151]
	s_cbranch_vccnz .LBB0_1456
	v_cvt_pk_bf16_f32 v152, v146, v147
	v_cvt_pk_bf16_f32 v153, v142, v143
	v_cvt_pk_bf16_f32 v154, v148, v149
	v_cvt_pk_bf16_f32 v155, v144, v145
	v_lshl_add_u64 v[156:157], v[150:151], 0, v[0:1]
	flat_store_dwordx4 v[156:157], v[152:155] sc1
.LBB0_1456:
	s_nop 1
	v_lshlrev_b32_e32 v152, 16, v138
	v_and_b32_e32 v153, 0xffff0000, v138
	v_lshlrev_b32_e32 v138, 16, v139
	v_and_b32_e32 v139, 0xffff0000, v139
	v_lshlrev_b32_e32 v154, 16, v140
	v_and_b32_e32 v155, 0xffff0000, v140
	v_lshlrev_b32_e32 v140, 16, v141
	v_and_b32_e32 v141, 0xffff0000, v141
	v_pk_fma_f32 v[138:139], v[92:93], s[62:63], v[138:139]
	v_pk_fma_f32 v[152:153], v[90:91], s[50:51], v[152:153]
	v_pk_fma_f32 v[140:141], v[84:85], s[62:63], v[140:141]
	s_and_b64 vcc, exec, s[48:49]
	v_pk_fma_f32 v[154:155], v[82:83], s[50:51], v[154:155]
	s_cbranch_vccnz .LBB0_1458
	v_cvt_pk_bf16_f32 v164, v152, v153
	v_cvt_pk_bf16_f32 v165, v138, v139
	v_cvt_pk_bf16_f32 v166, v154, v155
	v_cvt_pk_bf16_f32 v167, v140, v141
	v_lshl_add_u64 v[150:151], v[150:151], 0, v[0:1]
	flat_store_dwordx4 v[150:151], v[164:167] offset:256 sc1

; __device__ __forceinline__ unsigned pk2(float lo, float hi) { const f32x2 v = {lo, hi}; return __builtin_bit_cast(unsigned, __builtin_convertvector(v, hbf2)); }
;     __device__ __forceinline__ void operator()(const f32x4 (&acc)[2][2][4][2], const Unit& u, int wr, int wc, int fr, int fq, LAS f32x4* rsc, bool reuse) const {
;     ...
;                 for (int m = 0; m < 4; ++m) {
;                     const int row = row0 + ai * HALF + m * 16; float ss = 0.f;
; #pragma unroll
;                     for (int bj = 0; bj < 2; ++bj) {
;                         const size_t off = (size_t)row * DM + u.pn * BM + bj * HALF + cl;
;                         const f32x4 o0 = hv[m][bj][0] + acc[ai][bj][m][0] * alpha, o1 = hv[m][bj][1] + acc[ai][bj][m][1] * alpha;
;                         ss += (o0[0] * o0[0] + o0[1] * o0[1]) + (o0[2] * o0[2] + o0[3] * o0[3]) + (o1[0] * o1[0] + o1[1] * o1[1]) + (o1[2] * o1[2] + o1[3] * o1[3]);
;                         if (hb) { u32x4 w; w.x = pk2(o0[0], o0[1]); w.y = pk2(o0[2], o0[3]); w.z = pk2(o1[0], o1[1]); w.w = pk2(o1[2], o1[3]); *(u32x4*)(hb + off) = w; }
.LBB0_1460:
	s_or_b64 exec, exec, s[62:63]
	v_lshlrev_b32_e32 v138, 16, v134
	s_waitcnt lgkmcnt(0)
	v_and_b32_e32 v139, 0xffff0000, v134
	v_lshlrev_b32_e32 v134, 16, v135
	v_and_b32_e32 v135, 0xffff0000, v135
	v_lshlrev_b32_e32 v140, 16, v136
	v_and_b32_e32 v141, 0xffff0000, v136
	v_lshlrev_b32_e32 v136, 16, v137
	v_and_b32_e32 v137, 0xffff0000, v137
	s_mov_b32 s62, s50
	s_mov_b32 s63, s50
	v_lshl_add_u64 v[142:143], s[56:57], 0, v[162:163]
	v_pk_fma_f32 v[134:135], v[80:81], s[62:63], v[134:135]
	v_pk_fma_f32 v[138:139], v[78:79], s[50:51], v[138:139]
	v_pk_fma_f32 v[136:137], v[72:73], s[62:63], v[136:137]
	v_pk_fma_f32 v[140:141], v[70:71], s[50:51], v[140:141]
	s_and_b64 vcc, exec, s[48:49]
	v_lshl_add_u64 v[142:143], s[80:81], 1, v[142:143]
	s_cbranch_vccnz .LBB0_1462
	v_cvt_pk_bf16_f32 v144, v138, v139
	v_cvt_pk_bf16_f32 v145, v134, v135
	v_cvt_pk_bf16_f32 v146, v140, v141
	v_cvt_pk_bf16_f32 v147, v136, v137
	v_lshl_add_u64 v[148:149], v[142:143], 0, v[0:1]
	flat_store_dwordx4 v[148:149], v[144:147] sc1
.LBB0_1462:
	s_nop 1
	v_lshlrev_b32_e32 v144, 16, v130
	v_and_b32_e32 v145, 0xffff0000, v130
	v_lshlrev_b32_e32 v130, 16, v131
	v_and_b32_e32 v131, 0xffff0000, v131
	v_lshlrev_b32_e32 v146, 16, v132
	v_and_b32_e32 v147, 0xffff0000, v132
	v_lshlrev_b32_e32 v132, 16, v133
	v_and_b32_e32 v133, 0xffff0000, v133
	v_pk_fma_f32 v[130:131], v[76:77], s[62:63], v[130:131]
	v_pk_fma_f32 v[144:145], v[74:75], s[50:51], v[144:145]
	v_pk_fma_f32 v[132:133], v[68:69], s[62:63], v[132:133]
	s_and_b64 vcc, exec, s[48:49]
	v_pk_fma_f32 v[146:147], v[66:67], s[50:51], v[146:147]
	s_cbranch_vccnz .LBB0_1464
	v_cvt_pk_bf16_f32 v148, v144, v145
	v_cvt_pk_bf16_f32 v149, v130, v131
	v_cvt_pk_bf16_f32 v150, v146, v147
	v_cvt_pk_bf16_f32 v151, v132, v133
	v_lshl_add_u64 v[142:143], v[142:143], 0, v[0:1]
	flat_store_dwordx4 v[142:143], v[148:151] offset:256 sc1

; __device__ __forceinline__ unsigned pk2(float lo, float hi) { const f32x2 v = {lo, hi}; return __builtin_bit_cast(unsigned, __builtin_convertvector(v, hbf2)); }
;     __device__ __forceinline__ void operator()(const f32x4 (&acc)[2][2][4][2], const Unit& u, int wr, int wc, int fr, int fq, LAS f32x4* rsc, bool reuse) const {
;     ...
;                     u32x4 hr[4][2];
; #pragma unroll
;                     for (int m = 0; m < 4; ++m)
; #pragma unroll
;                         for (int bj = 0; bj < 2; ++bj) hr[m][bj] = *(const u32x4*)(hinb + (size_t)(row0 + ai * HALF + m * 16) * DM + u.pn * BM + bj * HALF + cl);
;                     asm volatile("" ::: "memory");
; #pragma unroll
;                     for (int m = 0; m < 4; ++m)
; #pragma unroll
;                         for (int bj = 0; bj < 2; ++bj) { const u32x4 r = hr[m][bj]; hv[m][bj][0] = (f32x4){bflo(r.x), bfhi(r.x), bflo(r.y), bfhi(r.y)}; hv[m][bj][1] = (f32x4){bflo(r.z), bfhi(r.z), bflo(r.w), bfhi(r.w)}; }
;                 }
; #pragma unroll
;                 for (int m = 0; m < 4; ++m) {
;                     const int row = row0 + ai * HALF + m * 16; float ss = 0.f;
; #pragma unroll
;                     for (int bj = 0; bj < 2; ++bj) {
;                         const size_t off = (size_t)row * DM + u.pn * BM + bj * HALF + cl;
;                         const f32x4 o0 = hv[m][bj][0] + acc[ai][bj][m][0] * alpha, o1 = hv[m][bj][1] + acc[ai][bj][m][1] * alpha;
;                         ss += (o0[0] * o0[0] + o0[1] * o0[1]) + (o0[2] * o0[2] + o0[3] * o0[3]) + (o1[0] * o1[0] + o1[1] * o1[1]) + (o1[2] * o1[2] + o1[3] * o1[3]);
;                         if (hb) { u32x4 w; w.x = pk2(o0[0], o0[1]); w.y = pk2(o0[2], o0[3]); w.z = pk2(o1[0], o1[1]); w.w = pk2(o1[2], o1[3]); *(u32x4*)(hb + off) = w; }
.LBB0_1466:
	s_or_b64 exec, exec, s[62:63]
	s_waitcnt lgkmcnt(0)
	v_lshlrev_b64 v[130:131], 12, v[210:211]
	s_mov_b64 s[62:63], 0x80000
	v_lshl_add_u64 v[172:173], v[130:131], 0, s[62:63]
	s_mov_b64 s[62:63], 0x90000
	v_lshl_add_u64 v[166:167], v[130:131], 0, s[62:63]
	s_mov_b64 s[62:63], 0xa0000
	v_lshl_add_u64 v[164:165], v[130:131], 0, s[62:63]
	s_mov_b64 s[62:63], 0xb0000
	v_lshl_add_u64 v[132:133], v[160:161], 0, v[172:173]
	v_lshl_add_u64 v[162:163], v[130:131], 0, s[62:63]
	v_lshl_add_u64 v[130:131], v[160:161], 0, v[166:167]
	v_lshl_add_u64 v[134:135], v[160:161], 0, v[164:165]
	flat_load_dwordx4 v[168:171], v[132:133]
	v_lshl_add_u64 v[160:161], v[160:161], 0, v[162:163]
	flat_load_dwordx4 v[154:157], v[132:133] offset:256
	flat_load_dwordx4 v[150:153], v[130:131]
	flat_load_dwordx4 v[146:149], v[130:131] offset:256
	flat_load_dwordx4 v[142:145], v[134:135]
	flat_load_dwordx4 v[138:141], v[134:135] offset:256
	s_nop 0
	flat_load_dwordx4 v[134:137], v[160:161]
	flat_load_dwordx4 v[130:133], v[160:161] offset:256
	s_mov_b32 s62, s50
	s_mov_b32 s63, s50
	v_lshl_add_u64 v[174:175], s[56:57], 0, v[172:173]
	s_and_b64 vcc, exec, s[48:49]
	v_lshl_add_u64 v[174:175], s[80:81], 1, v[174:175]
	s_waitcnt vmcnt(0) lgkmcnt(0)
	v_lshlrev_b32_e32 v160, 16, v168
	v_and_b32_e32 v161, 0xffff0000, v168
	v_lshlrev_b32_e32 v168, 16, v169
	v_and_b32_e32 v169, 0xffff0000, v169
	v_lshlrev_b32_e32 v176, 16, v170
	v_and_b32_e32 v177, 0xffff0000, v170
	v_lshlrev_b32_e32 v178, 16, v171
	v_and_b32_e32 v179, 0xffff0000, v171
	v_pk_fma_f32 v[170:171], v[64:65], s[62:63], v[168:169]
	v_pk_fma_f32 v[172:173], v[62:63], s[50:51], v[160:161]
	v_pk_fma_f32 v[160:161], v[56:57], s[62:63], v[178:179]
	v_pk_fma_f32 v[168:169], v[54:55], s[50:51], v[176:177]
	s_cbranch_vccnz .LBB0_1468
	v_cvt_pk_bf16_f32 v176, v172, v173
	v_cvt_pk_bf16_f32 v177, v170, v171
	v_cvt_pk_bf16_f32 v178, v168, v169
	v_cvt_pk_bf16_f32 v179, v160, v161
	v_lshl_add_u64 v[182:183], v[174:175], 0, v[0:1]
	flat_store_dwordx4 v[182:183], v[176:179] sc1
.LBB0_1468:
	s_nop 1
	v_lshlrev_b32_e32 v176, 16, v154
	v_and_b32_e32 v177, 0xffff0000, v154
	v_lshlrev_b32_e32 v154, 16, v155
	v_and_b32_e32 v155, 0xffff0000, v155
	v_lshlrev_b32_e32 v178, 16, v156
	v_and_b32_e32 v179, 0xffff0000, v156
	v_lshlrev_b32_e32 v156, 16, v157
	v_and_b32_e32 v157, 0xffff0000, v157
	v_pk_fma_f32 v[154:155], v[60:61], s[62:63], v[154:155]
	v_pk_fma_f32 v[176:177], v[58:59], s[50:51], v[176:177]
	v_pk_fma_f32 v[156:157], v[52:53], s[62:63], v[156:157]
	s_and_b64 vcc, exec, s[48:49]
	v_pk_fma_f32 v[178:179], v[50:51], s[50:51], v[178:179]
	s_cbranch_vccnz .LBB0_1470
	v_cvt_pk_bf16_f32 v182, v176, v177
	v_cvt_pk_bf16_f32 v183, v154, v155
	v_cvt_pk_bf16_f32 v184, v178, v179
	v_cvt_pk_bf16_f32 v185, v156, v157
	v_lshl_add_u64 v[174:175], v[174:175], 0, v[0:1]
	flat_store_dwordx4 v[174:175], v[182:185] offset:256 sc1

; __device__ __forceinline__ unsigned pk2(float lo, float hi) { const f32x2 v = {lo, hi}; return __builtin_bit_cast(unsigned, __builtin_convertvector(v, hbf2)); }
;     __device__ __forceinline__ void operator()(const f32x4 (&acc)[2][2][4][2], const Unit& u, int wr, int wc, int fr, int fq, LAS f32x4* rsc, bool reuse) const {
;     ...
;                 for (int m = 0; m < 4; ++m) {
;                     const int row = row0 + ai * HALF + m * 16; float ss = 0.f;
; #pragma unroll
;                     for (int bj = 0; bj < 2; ++bj) {
;                         const size_t off = (size_t)row * DM + u.pn * BM + bj * HALF + cl;
;                         const f32x4 o0 = hv[m][bj][0] + acc[ai][bj][m][0] * alpha, o1 = hv[m][bj][1] + acc[ai][bj][m][1] * alpha;
;                         ss += (o0[0] * o0[0] + o0[1] * o0[1]) + (o0[2] * o0[2] + o0[3] * o0[3]) + (o1[0] * o1[0] + o1[1] * o1[1]) + (o1[2] * o1[2] + o1[3] * o1[3]);
;                         if (hb) { u32x4 w; w.x = pk2(o0[0], o0[1]); w.y = pk2(o0[2], o0[3]); w.z = pk2(o1[0], o1[1]); w.w = pk2(o1[2], o1[3]); *(u32x4*)(hb + off) = w; }
.LBB0_1472:
	s_or_b64 exec, exec, s[62:63]
	v_lshlrev_b32_e32 v154, 16, v150
	s_waitcnt lgkmcnt(0)
	v_and_b32_e32 v155, 0xffff0000, v150
	v_lshlrev_b32_e32 v150, 16, v151
	v_and_b32_e32 v151, 0xffff0000, v151
	v_lshlrev_b32_e32 v156, 16, v152
	v_and_b32_e32 v157, 0xffff0000, v152
	v_lshlrev_b32_e32 v152, 16, v153
	v_and_b32_e32 v153, 0xffff0000, v153
	s_mov_b32 s62, s50
	s_mov_b32 s63, s50
	v_lshl_add_u64 v[160:161], s[56:57], 0, v[166:167]
	v_pk_fma_f32 v[150:151], v[48:49], s[62:63], v[150:151]
	v_pk_fma_f32 v[154:155], v[46:47], s[50:51], v[154:155]
	v_pk_fma_f32 v[152:153], v[40:41], s[62:63], v[152:153]
	v_pk_fma_f32 v[156:157], v[38:39], s[50:51], v[156:157]
	s_and_b64 vcc, exec, s[48:49]
	v_lshl_add_u64 v[160:161], s[80:81], 1, v[160:161]
	s_cbranch_vccnz .LBB0_1474
	v_cvt_pk_bf16_f32 v166, v154, v155
	v_cvt_pk_bf16_f32 v167, v150, v151
	v_cvt_pk_bf16_f32 v168, v156, v157
	v_cvt_pk_bf16_f32 v169, v152, v153
	v_lshl_add_u64 v[170:171], v[160:161], 0, v[0:1]
	flat_store_dwordx4 v[170:171], v[166:169] sc1
.LBB0_1474:
	s_nop 1
	v_lshlrev_b32_e32 v166, 16, v146
	v_and_b32_e32 v167, 0xffff0000, v146
	v_lshlrev_b32_e32 v146, 16, v147
	v_and_b32_e32 v147, 0xffff0000, v147
	v_lshlrev_b32_e32 v168, 16, v148
	v_and_b32_e32 v169, 0xffff0000, v148
	v_lshlrev_b32_e32 v148, 16, v149
	v_and_b32_e32 v149, 0xffff0000, v149
	v_pk_fma_f32 v[146:147], v[44:45], s[62:63], v[146:147]
	v_pk_fma_f32 v[166:167], v[42:43], s[50:51], v[166:167]
	v_pk_fma_f32 v[148:149], v[36:37], s[62:63], v[148:149]
	s_and_b64 vcc, exec, s[48:49]
	v_pk_fma_f32 v[168:169], v[34:35], s[50:51], v[168:169]
	s_cbranch_vccnz .LBB0_1476
	v_cvt_pk_bf16_f32 v170, v166, v167
	v_cvt_pk_bf16_f32 v171, v146, v147
	v_cvt_pk_bf16_f32 v172, v168, v169
	v_cvt_pk_bf16_f32 v173, v148, v149
	v_lshl_add_u64 v[160:161], v[160:161], 0, v[0:1]
	flat_store_dwordx4 v[160:161], v[170:173] offset:256 sc1

; __device__ __forceinline__ unsigned pk2(float lo, float hi) { const f32x2 v = {lo, hi}; return __builtin_bit_cast(unsigned, __builtin_convertvector(v, hbf2)); }
;     __device__ __forceinline__ void operator()(const f32x4 (&acc)[2][2][4][2], const Unit& u, int wr, int wc, int fr, int fq, LAS f32x4* rsc, bool reuse) const {
;     ...
;                 for (int m = 0; m < 4; ++m) {
;                     const int row = row0 + ai * HALF + m * 16; float ss = 0.f;
; #pragma unroll
;                     for (int bj = 0; bj < 2; ++bj) {
;                         const size_t off = (size_t)row * DM + u.pn * BM + bj * HALF + cl;
;                         const f32x4 o0 = hv[m][bj][0] + acc[ai][bj][m][0] * alpha, o1 = hv[m][bj][1] + acc[ai][bj][m][1] * alpha;
;                         ss += (o0[0] * o0[0] + o0[1] * o0[1]) + (o0[2] * o0[2] + o0[3] * o0[3]) + (o1[0] * o1[0] + o1[1] * o1[1]) + (o1[2] * o1[2] + o1[3] * o1[3]);
;                         if (hb) { u32x4 w; w.x = pk2(o0[0], o0[1]); w.y = pk2(o0[2], o0[3]); w.z = pk2(o1[0], o1[1]); w.w = pk2(o1[2], o1[3]); *(u32x4*)(hb + off) = w; }
.LBB0_1478:
	s_or_b64 exec, exec, s[62:63]
	v_lshlrev_b32_e32 v146, 16, v142
	s_waitcnt lgkmcnt(0)
	v_and_b32_e32 v147, 0xffff0000, v142
	v_lshlrev_b32_e32 v142, 16, v143
	v_and_b32_e32 v143, 0xffff0000, v143
	v_lshlrev_b32_e32 v148, 16, v144
	v_and_b32_e32 v149, 0xffff0000, v144
	v_lshlrev_b32_e32 v144, 16, v145
	v_and_b32_e32 v145, 0xffff0000, v145
	s_mov_b32 s62, s50
	s_mov_b32 s63, s50
	v_lshl_add_u64 v[150:151], s[56:57], 0, v[164:165]
	v_pk_fma_f32 v[142:143], v[32:33], s[62:63], v[142:143]
	v_pk_fma_f32 v[146:147], v[30:31], s[50:51], v[146:147]
	v_pk_fma_f32 v[144:145], v[24:25], s[62:63], v[144:145]
	v_pk_fma_f32 v[148:149], v[22:23], s[50:51], v[148:149]
	s_and_b64 vcc, exec, s[48:49]
	v_lshl_add_u64 v[150:151], s[80:81], 1, v[150:151]
	s_cbranch_vccnz .LBB0_1480
	v_cvt_pk_bf16_f32 v152, v146, v147
	v_cvt_pk_bf16_f32 v153, v142, v143
	v_cvt_pk_bf16_f32 v154, v148, v149
	v_cvt_pk_bf16_f32 v155, v144, v145
	v_lshl_add_u64 v[156:157], v[150:151], 0, v[0:1]
	flat_store_dwordx4 v[156:157], v[152:155] sc1
.LBB0_1480:
	s_nop 1
	v_lshlrev_b32_e32 v152, 16, v138
	v_and_b32_e32 v153, 0xffff0000, v138
	v_lshlrev_b32_e32 v138, 16, v139
	v_and_b32_e32 v139, 0xffff0000, v139
	v_lshlrev_b32_e32 v154, 16, v140
	v_and_b32_e32 v155, 0xffff0000, v140
	v_lshlrev_b32_e32 v140, 16, v141
	v_and_b32_e32 v141, 0xffff0000, v141
	v_pk_fma_f32 v[138:139], v[28:29], s[62:63], v[138:139]
	v_pk_fma_f32 v[152:153], v[26:27], s[50:51], v[152:153]
	v_pk_fma_f32 v[140:141], v[20:21], s[62:63], v[140:141]
	s_and_b64 vcc, exec, s[48:49]
	v_pk_fma_f32 v[154:155], v[18:19], s[50:51], v[154:155]
	s_cbranch_vccnz .LBB0_1482
	v_cvt_pk_bf16_f32 v164, v152, v153
	v_cvt_pk_bf16_f32 v165, v138, v139
	v_cvt_pk_bf16_f32 v166, v154, v155
	v_cvt_pk_bf16_f32 v167, v140, v141
	v_lshl_add_u64 v[150:151], v[150:151], 0, v[0:1]
	flat_store_dwordx4 v[150:151], v[164:167] offset:256 sc1

; __device__ __forceinline__ unsigned pk2(float lo, float hi) { const f32x2 v = {lo, hi}; return __builtin_bit_cast(unsigned, __builtin_convertvector(v, hbf2)); }
;     __device__ __forceinline__ void operator()(const f32x4 (&acc)[2][2][4][2], const Unit& u, int wr, int wc, int fr, int fq, LAS f32x4* rsc, bool reuse) const {
;     ...
;                 for (int m = 0; m < 4; ++m) {
;                     const int row = row0 + ai * HALF + m * 16; float ss = 0.f;
; #pragma unroll
;                     for (int bj = 0; bj < 2; ++bj) {
;                         const size_t off = (size_t)row * DM + u.pn * BM + bj * HALF + cl;
;                         const f32x4 o0 = hv[m][bj][0] + acc[ai][bj][m][0] * alpha, o1 = hv[m][bj][1] + acc[ai][bj][m][1] * alpha;
;                         ss += (o0[0] * o0[0] + o0[1] * o0[1]) + (o0[2] * o0[2] + o0[3] * o0[3]) + (o1[0] * o1[0] + o1[1] * o1[1]) + (o1[2] * o1[2] + o1[3] * o1[3]);
;                         if (hb) { u32x4 w; w.x = pk2(o0[0], o0[1]); w.y = pk2(o0[2], o0[3]); w.z = pk2(o1[0], o1[1]); w.w = pk2(o1[2], o1[3]); *(u32x4*)(hb + off) = w; }
.LBB0_1484:
	s_or_b64 exec, exec, s[62:63]
	v_lshlrev_b32_e32 v138, 16, v134
	s_waitcnt lgkmcnt(0)
	v_and_b32_e32 v139, 0xffff0000, v134
	v_lshlrev_b32_e32 v134, 16, v135
	v_and_b32_e32 v135, 0xffff0000, v135
	v_lshlrev_b32_e32 v140, 16, v136
	v_and_b32_e32 v141, 0xffff0000, v136
	v_lshlrev_b32_e32 v136, 16, v137
	v_and_b32_e32 v137, 0xffff0000, v137
	s_mov_b32 s62, s50
	s_mov_b32 s63, s50
	v_lshl_add_u64 v[142:143], s[56:57], 0, v[162:163]
	v_pk_fma_f32 v[134:135], v[16:17], s[62:63], v[134:135]
	v_pk_fma_f32 v[138:139], v[14:15], s[50:51], v[138:139]
	v_pk_fma_f32 v[136:137], v[8:9], s[62:63], v[136:137]
	v_pk_fma_f32 v[140:141], v[6:7], s[50:51], v[140:141]
	s_and_b64 vcc, exec, s[48:49]
	v_lshl_add_u64 v[142:143], s[80:81], 1, v[142:143]
	s_cbranch_vccnz .LBB0_1486
	v_cvt_pk_bf16_f32 v144, v138, v139
	v_cvt_pk_bf16_f32 v145, v134, v135
	v_cvt_pk_bf16_f32 v146, v140, v141
	v_cvt_pk_bf16_f32 v147, v136, v137
	v_lshl_add_u64 v[148:149], v[142:143], 0, v[0:1]
	flat_store_dwordx4 v[148:149], v[144:147] sc1
.LBB0_1486:
	s_nop 1
	v_lshlrev_b32_e32 v144, 16, v130
	v_and_b32_e32 v145, 0xffff0000, v130
	v_lshlrev_b32_e32 v130, 16, v131
	v_and_b32_e32 v131, 0xffff0000, v131
	v_lshlrev_b32_e32 v146, 16, v132
	v_and_b32_e32 v147, 0xffff0000, v132
	v_lshlrev_b32_e32 v132, 16, v133
	v_and_b32_e32 v133, 0xffff0000, v133
	v_pk_fma_f32 v[130:131], v[12:13], s[62:63], v[130:131]
	v_pk_fma_f32 v[144:145], v[10:11], s[50:51], v[144:145]
	v_pk_fma_f32 v[132:133], v[4:5], s[62:63], v[132:133]
	s_and_b64 vcc, exec, s[48:49]
	v_pk_fma_f32 v[146:147], v[2:3], s[50:51], v[146:147]
	v_readlane_b32 s69, v253, 16
	s_cbranch_vccnz .LBB0_1488
	v_cvt_pk_bf16_f32 v148, v144, v145
	v_cvt_pk_bf16_f32 v149, v130, v131
	v_cvt_pk_bf16_f32 v150, v146, v147
	v_cvt_pk_bf16_f32 v151, v132, v133
	v_lshl_add_u64 v[142:143], v[142:143], 0, v[0:1]
	flat_store_dwordx4 v[142:143], v[148:151] offset:256 sc1

; __device__ __forceinline__ unsigned pk2(float lo, float hi) { const f32x2 v = {lo, hi}; return __builtin_bit_cast(unsigned, __builtin_convertvector(v, hbf2)); }
;     __device__ __forceinline__ void operator()(const f32x4 (&acc)[2][2][4][2], const Unit& u, int wr, int wc, int fr, int fq, LAS f32x4* rsc, bool reuse) const {
;     ...
;                     u32x4 hr[4][2];
; #pragma unroll
;                     for (int m = 0; m < 4; ++m)
; #pragma unroll
;                         for (int bj = 0; bj < 2; ++bj) hr[m][bj] = *(const u32x4*)(hinb + (size_t)(row0 + ai * HALF + m * 16) * DM + u.pn * BM + bj * HALF + cl);
;                     asm volatile("" ::: "memory");
; #pragma unroll
;                     for (int m = 0; m < 4; ++m)
; #pragma unroll
;                         for (int bj = 0; bj < 2; ++bj) { const u32x4 r = hr[m][bj]; hv[m][bj][0] = (f32x4){bflo(r.x), bfhi(r.x), bflo(r.y), bfhi(r.y)}; hv[m][bj][1] = (f32x4){bflo(r.z), bfhi(r.z), bflo(r.w), bfhi(r.w)}; }
;                 }
; #pragma unroll
;                 for (int m = 0; m < 4; ++m) {
;                     const int row = row0 + ai * HALF + m * 16; float ss = 0.f;
; #pragma unroll
;                     for (int bj = 0; bj < 2; ++bj) {
;                         const size_t off = (size_t)row * DM + u.pn * BM + bj * HALF + cl;
;                         const f32x4 o0 = hv[m][bj][0] + acc[ai][bj][m][0] * alpha, o1 = hv[m][bj][1] + acc[ai][bj][m][1] * alpha;
;                         ss += (o0[0] * o0[0] + o0[1] * o0[1]) + (o0[2] * o0[2] + o0[3] * o0[3]) + (o1[0] * o1[0] + o1[1] * o1[1]) + (o1[2] * o1[2] + o1[3] * o1[3]);
;                         if (hb) { u32x4 w; w.x = pk2(o0[0], o0[1]); w.y = pk2(o0[2], o0[3]); w.z = pk2(o1[0], o1[1]); w.w = pk2(o1[2], o1[3]); *(u32x4*)(hb + off) = w; }
.LBB0_1854:
	s_lshl_b32 s22, s84, 8
	s_ashr_i32 s23, s22, 31
	s_lshl_b64 s[62:63], s[22:23], 1
	s_add_u32 s48, s48, s62
	s_addc_u32 s49, s3, s63
	v_lshlrev_b32_e32 v2, 1, v204
	v_ashrrev_i32_e32 v211, 31, v210
	v_lshl_add_u64 v[162:163], s[48:49], 0, v[2:3]
	v_lshlrev_b64 v[160:161], 12, v[210:211]
	v_lshl_add_u64 v[132:133], v[162:163], 0, v[160:161]
	flat_load_dwordx4 v[172:175], v[132:133]
	flat_load_dwordx4 v[156:159], v[132:133] offset:256
	v_or_b32_e32 v132, 16, v210
	v_ashrrev_i32_e32 v133, 31, v132
	v_lshlrev_b64 v[168:169], 12, v[132:133]
	v_lshl_add_u64 v[132:133], v[162:163], 0, v[168:169]
	flat_load_dwordx4 v[152:155], v[132:133]
	flat_load_dwordx4 v[148:151], v[132:133] offset:256
	v_or_b32_e32 v132, 32, v210
	v_ashrrev_i32_e32 v133, 31, v132
	v_lshlrev_b64 v[166:167], 12, v[132:133]
	v_lshl_add_u64 v[132:133], v[162:163], 0, v[166:167]
	flat_load_dwordx4 v[144:147], v[132:133]
	flat_load_dwordx4 v[140:143], v[132:133] offset:256
	v_or_b32_e32 v132, 48, v210
	v_ashrrev_i32_e32 v133, 31, v132
	v_lshlrev_b64 v[164:165], 12, v[132:133]
	v_lshl_add_u64 v[132:133], v[162:163], 0, v[164:165]
	flat_load_dwordx4 v[136:139], v[132:133]
	s_nop 0
	flat_load_dwordx4 v[132:135], v[132:133] offset:256
	v_lshl_add_u64 v[160:161], s[20:21], 0, v[160:161]
	s_cmp_lg_u64 s[20:21], 0
	v_lshl_add_u64 v[170:171], s[22:23], 1, v[160:161]
	s_cselect_b64 s[62:63], -1, 0
	s_and_b64 vcc, exec, s[62:63]
	s_waitcnt vmcnt(0) lgkmcnt(0)
	v_lshlrev_b32_e32 v160, 16, v172
	v_and_b32_e32 v161, 0xffff0000, v172
	v_lshlrev_b32_e32 v172, 16, v173
	v_and_b32_e32 v173, 0xffff0000, v173
	v_lshlrev_b32_e32 v178, 16, v174
	v_and_b32_e32 v179, 0xffff0000, v174
	v_lshlrev_b32_e32 v180, 16, v175
	v_and_b32_e32 v181, 0xffff0000, v175
	v_pk_fma_f32 v[174:175], v[130:131], s[52:53], v[172:173] op_sel_hi:[1,0,1]
	v_pk_fma_f32 v[176:177], v[128:129], s[52:53], v[160:161] op_sel_hi:[1,0,1]
	v_pk_fma_f32 v[160:161], v[122:123], s[52:53], v[180:181] op_sel_hi:[1,0,1]
	v_pk_fma_f32 v[172:173], v[120:121], s[52:53], v[178:179] op_sel_hi:[1,0,1]
	s_cbranch_vccz .LBB0_1856
	v_cvt_pk_bf16_f32 v178, v176, v177
	v_cvt_pk_bf16_f32 v179, v174, v175
	v_cvt_pk_bf16_f32 v180, v172, v173
	v_cvt_pk_bf16_f32 v181, v160, v161
	v_lshl_add_u64 v[182:183], v[170:171], 0, v[2:3]
	flat_store_dwordx4 v[182:183], v[178:181] sc1
.LBB0_1856:
	s_mov_b32 s53, s52
	s_nop 0
	v_lshlrev_b32_e32 v178, 16, v156
	v_and_b32_e32 v179, 0xffff0000, v156
	v_lshlrev_b32_e32 v156, 16, v157
	v_and_b32_e32 v157, 0xffff0000, v157
	v_lshlrev_b32_e32 v180, 16, v158
	v_and_b32_e32 v181, 0xffff0000, v158
	v_lshlrev_b32_e32 v158, 16, v159
	v_and_b32_e32 v159, 0xffff0000, v159
	s_mov_b32 s48, s52
	s_mov_b32 s49, s52
	v_cndmask_b32_e64 v182, 0, 1, s[62:63]
	v_pk_fma_f32 v[156:157], v[126:127], s[48:49], v[156:157]
	v_pk_fma_f32 v[178:179], v[124:125], s[52:53], v[178:179]
	v_pk_fma_f32 v[158:159], v[118:119], s[48:49], v[158:159]
	v_cmp_ne_u32_e64 s[48:49], 1, v182
	s_andn2_b64 vcc, exec, s[62:63]
	v_pk_fma_f32 v[180:181], v[116:117], s[52:53], v[180:181]
	s_cbranch_vccnz .LBB0_1858
	v_cvt_pk_bf16_f32 v182, v178, v179
	v_cvt_pk_bf16_f32 v183, v156, v157
	v_cvt_pk_bf16_f32 v184, v180, v181
	v_cvt_pk_bf16_f32 v185, v158, v159
	v_lshl_add_u64 v[170:171], v[170:171], 0, v[2:3]
	flat_store_dwordx4 v[170:171], v[182:185] offset:256 sc1

; __device__ __forceinline__ unsigned pk2(float lo, float hi) { const f32x2 v = {lo, hi}; return __builtin_bit_cast(unsigned, __builtin_convertvector(v, hbf2)); }
;     __device__ __forceinline__ void operator()(const f32x4 (&acc)[2][2][4][2], const Unit& u, int wr, int wc, int fr, int fq, LAS f32x4* rsc, bool reuse) const {
;     ...
;                 for (int m = 0; m < 4; ++m) {
;                     const int row = row0 + ai * HALF + m * 16; float ss = 0.f;
; #pragma unroll
;                     for (int bj = 0; bj < 2; ++bj) {
;                         const size_t off = (size_t)row * DM + u.pn * BM + bj * HALF + cl;
;                         const f32x4 o0 = hv[m][bj][0] + acc[ai][bj][m][0] * alpha, o1 = hv[m][bj][1] + acc[ai][bj][m][1] * alpha;
;                         ss += (o0[0] * o0[0] + o0[1] * o0[1]) + (o0[2] * o0[2] + o0[3] * o0[3]) + (o1[0] * o1[0] + o1[1] * o1[1]) + (o1[2] * o1[2] + o1[3] * o1[3]);
;                         if (hb) { u32x4 w; w.x = pk2(o0[0], o0[1]); w.y = pk2(o0[2], o0[3]); w.z = pk2(o1[0], o1[1]); w.w = pk2(o1[2], o1[3]); *(u32x4*)(hb + off) = w; }
.LBB0_1860:
	s_or_b64 exec, exec, s[24:25]
	v_lshlrev_b32_e32 v156, 16, v152
	s_waitcnt lgkmcnt(0)
	v_and_b32_e32 v157, 0xffff0000, v152
	v_lshlrev_b32_e32 v152, 16, v153
	v_and_b32_e32 v153, 0xffff0000, v153
	v_lshlrev_b32_e32 v158, 16, v154
	v_and_b32_e32 v159, 0xffff0000, v154
	v_lshlrev_b32_e32 v154, 16, v155
	v_and_b32_e32 v155, 0xffff0000, v155
	s_mov_b32 s24, s52
	s_mov_b32 s25, s52
	v_lshl_add_u64 v[168:169], s[20:21], 0, v[168:169]
	v_pk_fma_f32 v[152:153], v[114:115], s[24:25], v[152:153]
	v_pk_fma_f32 v[156:157], v[112:113], s[52:53], v[156:157]
	v_pk_fma_f32 v[154:155], v[106:107], s[24:25], v[154:155]
	v_pk_fma_f32 v[158:159], v[104:105], s[52:53], v[158:159]
	s_and_b64 vcc, exec, s[48:49]
	v_lshl_add_u64 v[168:169], s[22:23], 1, v[168:169]
	s_cbranch_vccnz .LBB0_1862
	v_cvt_pk_bf16_f32 v170, v156, v157
	v_cvt_pk_bf16_f32 v171, v152, v153
	v_cvt_pk_bf16_f32 v172, v158, v159
	v_cvt_pk_bf16_f32 v173, v154, v155
	v_lshl_add_u64 v[174:175], v[168:169], 0, v[2:3]
	flat_store_dwordx4 v[174:175], v[170:173] sc1
.LBB0_1862:
	s_nop 1
	v_lshlrev_b32_e32 v170, 16, v148
	v_and_b32_e32 v171, 0xffff0000, v148
	v_lshlrev_b32_e32 v148, 16, v149
	v_and_b32_e32 v149, 0xffff0000, v149
	v_lshlrev_b32_e32 v172, 16, v150
	v_and_b32_e32 v173, 0xffff0000, v150
	v_lshlrev_b32_e32 v150, 16, v151
	v_and_b32_e32 v151, 0xffff0000, v151
	v_pk_fma_f32 v[148:149], v[110:111], s[24:25], v[148:149]
	v_pk_fma_f32 v[170:171], v[108:109], s[52:53], v[170:171]
	v_pk_fma_f32 v[150:151], v[102:103], s[24:25], v[150:151]
	s_and_b64 vcc, exec, s[48:49]
	v_pk_fma_f32 v[172:173], v[100:101], s[52:53], v[172:173]
	s_cbranch_vccnz .LBB0_1864
	v_cvt_pk_bf16_f32 v174, v170, v171
	v_cvt_pk_bf16_f32 v175, v148, v149
	v_cvt_pk_bf16_f32 v176, v172, v173
	v_cvt_pk_bf16_f32 v177, v150, v151
	v_lshl_add_u64 v[168:169], v[168:169], 0, v[2:3]
	flat_store_dwordx4 v[168:169], v[174:177] offset:256 sc1

; __device__ __forceinline__ unsigned pk2(float lo, float hi) { const f32x2 v = {lo, hi}; return __builtin_bit_cast(unsigned, __builtin_convertvector(v, hbf2)); }
;     __device__ __forceinline__ void operator()(const f32x4 (&acc)[2][2][4][2], const Unit& u, int wr, int wc, int fr, int fq, LAS f32x4* rsc, bool reuse) const {
;     ...
; #pragma unroll
;                 for (int m = 0; m < 4; ++m) {
;                     const int row = row0 + ai * HALF + m * 16; float ss = 0.f;
; #pragma unroll
;                     for (int bj = 0; bj < 2; ++bj) {
;                         const size_t off = (size_t)row * DM + u.pn * BM + bj * HALF + cl;
;                         const f32x4 o0 = hv[m][bj][0] + acc[ai][bj][m][0] * alpha, o1 = hv[m][bj][1] + acc[ai][bj][m][1] * alpha;
;                         ss += (o0[0] * o0[0] + o0[1] * o0[1]) + (o0[2] * o0[2] + o0[3] * o0[3]) + (o1[0] * o1[0] + o1[1] * o1[1]) + (o1[2] * o1[2] + o1[3] * o1[3]);
;                         if (hb) { u32x4 w; w.x = pk2(o0[0], o0[1]); w.y = pk2(o0[2], o0[3]); w.z = pk2(o1[0], o1[1]); w.w = pk2(o1[2], o1[3]); *(u32x4*)(hb + off) = w; }
.LBB0_1866:
	s_or_b64 exec, exec, s[24:25]
	v_lshlrev_b32_e32 v148, 16, v144
	s_waitcnt lgkmcnt(0)
	v_and_b32_e32 v149, 0xffff0000, v144
	v_lshlrev_b32_e32 v144, 16, v145
	v_and_b32_e32 v145, 0xffff0000, v145
	v_lshlrev_b32_e32 v150, 16, v146
	v_and_b32_e32 v151, 0xffff0000, v146
	v_lshlrev_b32_e32 v146, 16, v147
	v_and_b32_e32 v147, 0xffff0000, v147
	s_mov_b32 s24, s52
	s_mov_b32 s25, s52
	v_lshl_add_u64 v[152:153], s[20:21], 0, v[166:167]
	v_pk_fma_f32 v[144:145], v[98:99], s[24:25], v[144:145]
	v_pk_fma_f32 v[148:149], v[96:97], s[52:53], v[148:149]
	v_pk_fma_f32 v[146:147], v[90:91], s[24:25], v[146:147]
	v_pk_fma_f32 v[150:151], v[88:89], s[52:53], v[150:151]
	s_and_b64 vcc, exec, s[48:49]
	v_lshl_add_u64 v[152:153], s[22:23], 1, v[152:153]
	s_cbranch_vccnz .LBB0_1868
	v_cvt_pk_bf16_f32 v154, v148, v149
	v_cvt_pk_bf16_f32 v155, v144, v145
	v_cvt_pk_bf16_f32 v156, v150, v151
	v_cvt_pk_bf16_f32 v157, v146, v147
	v_lshl_add_u64 v[158:159], v[152:153], 0, v[2:3]
	flat_store_dwordx4 v[158:159], v[154:157] sc1
.LBB0_1868:
	s_nop 1
	v_lshlrev_b32_e32 v154, 16, v140
	v_and_b32_e32 v155, 0xffff0000, v140
	v_lshlrev_b32_e32 v140, 16, v141
	v_and_b32_e32 v141, 0xffff0000, v141
	v_lshlrev_b32_e32 v156, 16, v142
	v_and_b32_e32 v157, 0xffff0000, v142
	v_lshlrev_b32_e32 v142, 16, v143
	v_and_b32_e32 v143, 0xffff0000, v143
	v_pk_fma_f32 v[140:141], v[94:95], s[24:25], v[140:141]
	v_pk_fma_f32 v[154:155], v[92:93], s[52:53], v[154:155]
	v_pk_fma_f32 v[142:143], v[86:87], s[24:25], v[142:143]
	s_and_b64 vcc, exec, s[48:49]
	v_pk_fma_f32 v[156:157], v[84:85], s[52:53], v[156:157]
	s_cbranch_vccnz .LBB0_1870
	v_cvt_pk_bf16_f32 v166, v154, v155
	v_cvt_pk_bf16_f32 v167, v140, v141
	v_cvt_pk_bf16_f32 v168, v156, v157
	v_cvt_pk_bf16_f32 v169, v142, v143
	v_lshl_add_u64 v[152:153], v[152:153], 0, v[2:3]
	flat_store_dwordx4 v[152:153], v[166:169] offset:256 sc1

; __device__ __forceinline__ unsigned pk2(float lo, float hi) { const f32x2 v = {lo, hi}; return __builtin_bit_cast(unsigned, __builtin_convertvector(v, hbf2)); }
;     __device__ __forceinline__ void operator()(const f32x4 (&acc)[2][2][4][2], const Unit& u, int wr, int wc, int fr, int fq, LAS f32x4* rsc, bool reuse) const {
;     ...
; #pragma unroll
;                 for (int m = 0; m < 4; ++m) {
;                     const int row = row0 + ai * HALF + m * 16; float ss = 0.f;
; #pragma unroll
;                     for (int bj = 0; bj < 2; ++bj) {
;                         const size_t off = (size_t)row * DM + u.pn * BM + bj * HALF + cl;
;                         const f32x4 o0 = hv[m][bj][0] + acc[ai][bj][m][0] * alpha, o1 = hv[m][bj][1] + acc[ai][bj][m][1] * alpha;
;                         ss += (o0[0] * o0[0] + o0[1] * o0[1]) + (o0[2] * o0[2] + o0[3] * o0[3]) + (o1[0] * o1[0] + o1[1] * o1[1]) + (o1[2] * o1[2] + o1[3] * o1[3]);
;                         if (hb) { u32x4 w; w.x = pk2(o0[0], o0[1]); w.y = pk2(o0[2], o0[3]); w.z = pk2(o1[0], o1[1]); w.w = pk2(o1[2], o1[3]); *(u32x4*)(hb + off) = w; }
.LBB0_1872:
	s_or_b64 exec, exec, s[24:25]
	v_lshlrev_b32_e32 v140, 16, v136
	s_waitcnt lgkmcnt(0)
	v_and_b32_e32 v141, 0xffff0000, v136
	v_lshlrev_b32_e32 v136, 16, v137
	v_and_b32_e32 v137, 0xffff0000, v137
	v_lshlrev_b32_e32 v142, 16, v138
	v_and_b32_e32 v143, 0xffff0000, v138
	v_lshlrev_b32_e32 v138, 16, v139
	v_and_b32_e32 v139, 0xffff0000, v139
	s_mov_b32 s24, s52
	s_mov_b32 s25, s52
	v_lshl_add_u64 v[144:145], s[20:21], 0, v[164:165]
	v_pk_fma_f32 v[136:137], v[82:83], s[24:25], v[136:137]
	v_pk_fma_f32 v[140:141], v[80:81], s[52:53], v[140:141]
	v_pk_fma_f32 v[138:139], v[74:75], s[24:25], v[138:139]
	v_pk_fma_f32 v[142:143], v[72:73], s[52:53], v[142:143]
	s_and_b64 vcc, exec, s[48:49]
	v_lshl_add_u64 v[144:145], s[22:23], 1, v[144:145]
	s_cbranch_vccnz .LBB0_1874
	v_cvt_pk_bf16_f32 v146, v140, v141
	v_cvt_pk_bf16_f32 v147, v136, v137
	v_cvt_pk_bf16_f32 v148, v142, v143
	v_cvt_pk_bf16_f32 v149, v138, v139
	v_lshl_add_u64 v[150:151], v[144:145], 0, v[2:3]
	flat_store_dwordx4 v[150:151], v[146:149] sc1
.LBB0_1874:
	s_nop 1
	v_lshlrev_b32_e32 v146, 16, v132
	v_and_b32_e32 v147, 0xffff0000, v132
	v_lshlrev_b32_e32 v132, 16, v133
	v_and_b32_e32 v133, 0xffff0000, v133
	v_lshlrev_b32_e32 v148, 16, v134
	v_and_b32_e32 v149, 0xffff0000, v134
	v_lshlrev_b32_e32 v134, 16, v135
	v_and_b32_e32 v135, 0xffff0000, v135
	v_pk_fma_f32 v[132:133], v[78:79], s[24:25], v[132:133]
	v_pk_fma_f32 v[146:147], v[76:77], s[52:53], v[146:147]
	v_pk_fma_f32 v[134:135], v[70:71], s[24:25], v[134:135]
	s_and_b64 vcc, exec, s[48:49]
	v_pk_fma_f32 v[148:149], v[68:69], s[52:53], v[148:149]
	s_cbranch_vccnz .LBB0_1876
	v_cvt_pk_bf16_f32 v150, v146, v147
	v_cvt_pk_bf16_f32 v151, v132, v133
	v_cvt_pk_bf16_f32 v152, v148, v149
	v_cvt_pk_bf16_f32 v153, v134, v135
	v_lshl_add_u64 v[144:145], v[144:145], 0, v[2:3]
	flat_store_dwordx4 v[144:145], v[150:153] offset:256 sc1

; __device__ __forceinline__ unsigned pk2(float lo, float hi) { const f32x2 v = {lo, hi}; return __builtin_bit_cast(unsigned, __builtin_convertvector(v, hbf2)); }
;     __device__ __forceinline__ void operator()(const f32x4 (&acc)[2][2][4][2], const Unit& u, int wr, int wc, int fr, int fq, LAS f32x4* rsc, bool reuse) const {
;     ...
;                     u32x4 hr[4][2];
; #pragma unroll
;                     for (int m = 0; m < 4; ++m)
; #pragma unroll
;                         for (int bj = 0; bj < 2; ++bj) hr[m][bj] = *(const u32x4*)(hinb + (size_t)(row0 + ai * HALF + m * 16) * DM + u.pn * BM + bj * HALF + cl);
;                     asm volatile("" ::: "memory");
; #pragma unroll
;                     for (int m = 0; m < 4; ++m)
; #pragma unroll
;                         for (int bj = 0; bj < 2; ++bj) { const u32x4 r = hr[m][bj]; hv[m][bj][0] = (f32x4){bflo(r.x), bfhi(r.x), bflo(r.y), bfhi(r.y)}; hv[m][bj][1] = (f32x4){bflo(r.z), bfhi(r.z), bflo(r.w), bfhi(r.w)}; }
;                 }
; #pragma unroll
;                 for (int m = 0; m < 4; ++m) {
;                     const int row = row0 + ai * HALF + m * 16; float ss = 0.f;
; #pragma unroll
;                     for (int bj = 0; bj < 2; ++bj) {
;                         const size_t off = (size_t)row * DM + u.pn * BM + bj * HALF + cl;
;                         const f32x4 o0 = hv[m][bj][0] + acc[ai][bj][m][0] * alpha, o1 = hv[m][bj][1] + acc[ai][bj][m][1] * alpha;
;                         ss += (o0[0] * o0[0] + o0[1] * o0[1]) + (o0[2] * o0[2] + o0[3] * o0[3]) + (o1[0] * o1[0] + o1[1] * o1[1]) + (o1[2] * o1[2] + o1[3] * o1[3]);
;                         if (hb) { u32x4 w; w.x = pk2(o0[0], o0[1]); w.y = pk2(o0[2], o0[3]); w.z = pk2(o1[0], o1[1]); w.w = pk2(o1[2], o1[3]); *(u32x4*)(hb + off) = w; }
.LBB0_1878:
	s_or_b64 exec, exec, s[24:25]
	s_waitcnt lgkmcnt(0)
	v_lshlrev_b64 v[132:133], 12, v[210:211]
	s_mov_b64 s[24:25], 0x80000
	v_lshl_add_u64 v[174:175], v[132:133], 0, s[24:25]
	s_mov_b64 s[24:25], 0x90000
	v_lshl_add_u64 v[168:169], v[132:133], 0, s[24:25]
	s_mov_b64 s[24:25], 0xa0000
	v_lshl_add_u64 v[166:167], v[132:133], 0, s[24:25]
	s_mov_b64 s[24:25], 0xb0000
	v_lshl_add_u64 v[134:135], v[162:163], 0, v[174:175]
	v_lshl_add_u64 v[164:165], v[132:133], 0, s[24:25]
	v_lshl_add_u64 v[132:133], v[162:163], 0, v[168:169]
	v_lshl_add_u64 v[136:137], v[162:163], 0, v[166:167]
	flat_load_dwordx4 v[170:173], v[134:135]
	v_lshl_add_u64 v[162:163], v[162:163], 0, v[164:165]
	flat_load_dwordx4 v[156:159], v[134:135] offset:256
	flat_load_dwordx4 v[152:155], v[132:133]
	flat_load_dwordx4 v[148:151], v[132:133] offset:256
	flat_load_dwordx4 v[144:147], v[136:137]
	flat_load_dwordx4 v[140:143], v[136:137] offset:256
	s_nop 0
	flat_load_dwordx4 v[136:139], v[162:163]
	flat_load_dwordx4 v[132:135], v[162:163] offset:256
	s_mov_b32 s24, s52
	s_mov_b32 s25, s52
	v_lshl_add_u64 v[176:177], s[20:21], 0, v[174:175]
	s_and_b64 vcc, exec, s[48:49]
	v_lshl_add_u64 v[176:177], s[22:23], 1, v[176:177]
	s_waitcnt vmcnt(0) lgkmcnt(0)
	v_lshlrev_b32_e32 v162, 16, v170
	v_and_b32_e32 v163, 0xffff0000, v170
	v_lshlrev_b32_e32 v170, 16, v171
	v_and_b32_e32 v171, 0xffff0000, v171
	v_lshlrev_b32_e32 v178, 16, v172
	v_and_b32_e32 v179, 0xffff0000, v172
	v_lshlrev_b32_e32 v180, 16, v173
	v_and_b32_e32 v181, 0xffff0000, v173
	v_pk_fma_f32 v[172:173], v[66:67], s[24:25], v[170:171]
	v_pk_fma_f32 v[174:175], v[64:65], s[52:53], v[162:163]
	v_pk_fma_f32 v[162:163], v[58:59], s[24:25], v[180:181]
	v_pk_fma_f32 v[170:171], v[56:57], s[52:53], v[178:179]
	s_cbranch_vccnz .LBB0_1880
	v_cvt_pk_bf16_f32 v178, v174, v175
	v_cvt_pk_bf16_f32 v179, v172, v173
	v_cvt_pk_bf16_f32 v180, v170, v171
	v_cvt_pk_bf16_f32 v181, v162, v163
	v_lshl_add_u64 v[184:185], v[176:177], 0, v[2:3]
	flat_store_dwordx4 v[184:185], v[178:181] sc1
.LBB0_1880:
	s_nop 1
	v_lshlrev_b32_e32 v178, 16, v156
	v_and_b32_e32 v179, 0xffff0000, v156
	v_lshlrev_b32_e32 v156, 16, v157
	v_and_b32_e32 v157, 0xffff0000, v157
	v_lshlrev_b32_e32 v180, 16, v158
	v_and_b32_e32 v181, 0xffff0000, v158
	v_lshlrev_b32_e32 v158, 16, v159
	v_and_b32_e32 v159, 0xffff0000, v159
	v_pk_fma_f32 v[156:157], v[62:63], s[24:25], v[156:157]
	v_pk_fma_f32 v[178:179], v[60:61], s[52:53], v[178:179]
	v_pk_fma_f32 v[158:159], v[54:55], s[24:25], v[158:159]
	s_and_b64 vcc, exec, s[48:49]
	v_pk_fma_f32 v[180:181], v[52:53], s[52:53], v[180:181]
	s_cbranch_vccnz .LBB0_1882
	v_cvt_pk_bf16_f32 v184, v178, v179
	v_cvt_pk_bf16_f32 v185, v156, v157
	v_cvt_pk_bf16_f32 v186, v180, v181
	v_cvt_pk_bf16_f32 v187, v158, v159
	v_lshl_add_u64 v[176:177], v[176:177], 0, v[2:3]
	flat_store_dwordx4 v[176:177], v[184:187] offset:256 sc1

; __device__ __forceinline__ unsigned pk2(float lo, float hi) { const f32x2 v = {lo, hi}; return __builtin_bit_cast(unsigned, __builtin_convertvector(v, hbf2)); }
;     __device__ __forceinline__ void operator()(const f32x4 (&acc)[2][2][4][2], const Unit& u, int wr, int wc, int fr, int fq, LAS f32x4* rsc, bool reuse) const {
;     ...
; #pragma unroll
;                 for (int m = 0; m < 4; ++m) {
;                     const int row = row0 + ai * HALF + m * 16; float ss = 0.f;
; #pragma unroll
;                     for (int bj = 0; bj < 2; ++bj) {
;                         const size_t off = (size_t)row * DM + u.pn * BM + bj * HALF + cl;
;                         const f32x4 o0 = hv[m][bj][0] + acc[ai][bj][m][0] * alpha, o1 = hv[m][bj][1] + acc[ai][bj][m][1] * alpha;
;                         ss += (o0[0] * o0[0] + o0[1] * o0[1]) + (o0[2] * o0[2] + o0[3] * o0[3]) + (o1[0] * o1[0] + o1[1] * o1[1]) + (o1[2] * o1[2] + o1[3] * o1[3]);
;                         if (hb) { u32x4 w; w.x = pk2(o0[0], o0[1]); w.y = pk2(o0[2], o0[3]); w.z = pk2(o1[0], o1[1]); w.w = pk2(o1[2], o1[3]); *(u32x4*)(hb + off) = w; }
.LBB0_1884:
	s_or_b64 exec, exec, s[24:25]
	v_lshlrev_b32_e32 v156, 16, v152
	s_waitcnt lgkmcnt(0)
	v_and_b32_e32 v157, 0xffff0000, v152
	v_lshlrev_b32_e32 v152, 16, v153
	v_and_b32_e32 v153, 0xffff0000, v153
	v_lshlrev_b32_e32 v158, 16, v154
	v_and_b32_e32 v159, 0xffff0000, v154
	v_lshlrev_b32_e32 v154, 16, v155
	v_and_b32_e32 v155, 0xffff0000, v155
	s_mov_b32 s24, s52
	s_mov_b32 s25, s52
	v_lshl_add_u64 v[162:163], s[20:21], 0, v[168:169]
	v_pk_fma_f32 v[152:153], v[50:51], s[24:25], v[152:153]
	v_pk_fma_f32 v[156:157], v[48:49], s[52:53], v[156:157]
	v_pk_fma_f32 v[154:155], v[42:43], s[24:25], v[154:155]
	v_pk_fma_f32 v[158:159], v[40:41], s[52:53], v[158:159]
	s_and_b64 vcc, exec, s[48:49]
	v_lshl_add_u64 v[162:163], s[22:23], 1, v[162:163]
	s_cbranch_vccnz .LBB0_1886
	v_cvt_pk_bf16_f32 v168, v156, v157
	v_cvt_pk_bf16_f32 v169, v152, v153
	v_cvt_pk_bf16_f32 v170, v158, v159
	v_cvt_pk_bf16_f32 v171, v154, v155
	v_lshl_add_u64 v[172:173], v[162:163], 0, v[2:3]
	flat_store_dwordx4 v[172:173], v[168:171] sc1
.LBB0_1886:
	s_nop 1
	v_lshlrev_b32_e32 v168, 16, v148
	v_and_b32_e32 v169, 0xffff0000, v148
	v_lshlrev_b32_e32 v148, 16, v149
	v_and_b32_e32 v149, 0xffff0000, v149
	v_lshlrev_b32_e32 v170, 16, v150
	v_and_b32_e32 v171, 0xffff0000, v150
	v_lshlrev_b32_e32 v150, 16, v151
	v_and_b32_e32 v151, 0xffff0000, v151
	v_pk_fma_f32 v[148:149], v[46:47], s[24:25], v[148:149]
	v_pk_fma_f32 v[168:169], v[44:45], s[52:53], v[168:169]
	v_pk_fma_f32 v[150:151], v[38:39], s[24:25], v[150:151]
	s_and_b64 vcc, exec, s[48:49]
	v_pk_fma_f32 v[170:171], v[36:37], s[52:53], v[170:171]
	s_cbranch_vccnz .LBB0_1888
	v_cvt_pk_bf16_f32 v172, v168, v169
	v_cvt_pk_bf16_f32 v173, v148, v149
	v_cvt_pk_bf16_f32 v174, v170, v171
	v_cvt_pk_bf16_f32 v175, v150, v151
	v_lshl_add_u64 v[162:163], v[162:163], 0, v[2:3]
	flat_store_dwordx4 v[162:163], v[172:175] offset:256 sc1

; __device__ __forceinline__ unsigned pk2(float lo, float hi) { const f32x2 v = {lo, hi}; return __builtin_bit_cast(unsigned, __builtin_convertvector(v, hbf2)); }
;     __device__ __forceinline__ void operator()(const f32x4 (&acc)[2][2][4][2], const Unit& u, int wr, int wc, int fr, int fq, LAS f32x4* rsc, bool reuse) const {
;     ...
; #pragma unroll
;                 for (int m = 0; m < 4; ++m) {
;                     const int row = row0 + ai * HALF + m * 16; float ss = 0.f;
; #pragma unroll
;                     for (int bj = 0; bj < 2; ++bj) {
;                         const size_t off = (size_t)row * DM + u.pn * BM + bj * HALF + cl;
;                         const f32x4 o0 = hv[m][bj][0] + acc[ai][bj][m][0] * alpha, o1 = hv[m][bj][1] + acc[ai][bj][m][1] * alpha;
;                         ss += (o0[0] * o0[0] + o0[1] * o0[1]) + (o0[2] * o0[2] + o0[3] * o0[3]) + (o1[0] * o1[0] + o1[1] * o1[1]) + (o1[2] * o1[2] + o1[3] * o1[3]);
;                         if (hb) { u32x4 w; w.x = pk2(o0[0], o0[1]); w.y = pk2(o0[2], o0[3]); w.z = pk2(o1[0], o1[1]); w.w = pk2(o1[2], o1[3]); *(u32x4*)(hb + off) = w; }
.LBB0_1890:
	s_or_b64 exec, exec, s[24:25]
	v_lshlrev_b32_e32 v148, 16, v144
	s_waitcnt lgkmcnt(0)
	v_and_b32_e32 v149, 0xffff0000, v144
	v_lshlrev_b32_e32 v144, 16, v145
	v_and_b32_e32 v145, 0xffff0000, v145
	v_lshlrev_b32_e32 v150, 16, v146
	v_and_b32_e32 v151, 0xffff0000, v146
	v_lshlrev_b32_e32 v146, 16, v147
	v_and_b32_e32 v147, 0xffff0000, v147
	s_mov_b32 s24, s52
	s_mov_b32 s25, s52
	v_lshl_add_u64 v[152:153], s[20:21], 0, v[166:167]
	v_pk_fma_f32 v[144:145], v[34:35], s[24:25], v[144:145]
	v_pk_fma_f32 v[148:149], v[32:33], s[52:53], v[148:149]
	v_pk_fma_f32 v[146:147], v[26:27], s[24:25], v[146:147]
	v_pk_fma_f32 v[150:151], v[24:25], s[52:53], v[150:151]
	s_and_b64 vcc, exec, s[48:49]
	v_lshl_add_u64 v[152:153], s[22:23], 1, v[152:153]
	s_cbranch_vccnz .LBB0_1892
	v_cvt_pk_bf16_f32 v154, v148, v149
	v_cvt_pk_bf16_f32 v155, v144, v145
	v_cvt_pk_bf16_f32 v156, v150, v151
	v_cvt_pk_bf16_f32 v157, v146, v147
	v_lshl_add_u64 v[158:159], v[152:153], 0, v[2:3]
	flat_store_dwordx4 v[158:159], v[154:157] sc1
.LBB0_1892:
	s_nop 1
	v_lshlrev_b32_e32 v154, 16, v140
	v_and_b32_e32 v155, 0xffff0000, v140
	v_lshlrev_b32_e32 v140, 16, v141
	v_and_b32_e32 v141, 0xffff0000, v141
	v_lshlrev_b32_e32 v156, 16, v142
	v_and_b32_e32 v157, 0xffff0000, v142
	v_lshlrev_b32_e32 v142, 16, v143
	v_and_b32_e32 v143, 0xffff0000, v143
	v_pk_fma_f32 v[140:141], v[30:31], s[24:25], v[140:141]
	v_pk_fma_f32 v[154:155], v[28:29], s[52:53], v[154:155]
	v_pk_fma_f32 v[142:143], v[22:23], s[24:25], v[142:143]
	s_and_b64 vcc, exec, s[48:49]
	v_pk_fma_f32 v[156:157], v[20:21], s[52:53], v[156:157]
	s_cbranch_vccnz .LBB0_1894
	v_cvt_pk_bf16_f32 v166, v154, v155
	v_cvt_pk_bf16_f32 v167, v140, v141
	v_cvt_pk_bf16_f32 v168, v156, v157
	v_cvt_pk_bf16_f32 v169, v142, v143
	v_lshl_add_u64 v[152:153], v[152:153], 0, v[2:3]
	flat_store_dwordx4 v[152:153], v[166:169] offset:256 sc1

; __device__ __forceinline__ unsigned pk2(float lo, float hi) { const f32x2 v = {lo, hi}; return __builtin_bit_cast(unsigned, __builtin_convertvector(v, hbf2)); }
;     __device__ __forceinline__ void operator()(const f32x4 (&acc)[2][2][4][2], const Unit& u, int wr, int wc, int fr, int fq, LAS f32x4* rsc, bool reuse) const {
;     ...
; #pragma unroll
;                 for (int m = 0; m < 4; ++m) {
;                     const int row = row0 + ai * HALF + m * 16; float ss = 0.f;
; #pragma unroll
;                     for (int bj = 0; bj < 2; ++bj) {
;                         const size_t off = (size_t)row * DM + u.pn * BM + bj * HALF + cl;
;                         const f32x4 o0 = hv[m][bj][0] + acc[ai][bj][m][0] * alpha, o1 = hv[m][bj][1] + acc[ai][bj][m][1] * alpha;
;                         ss += (o0[0] * o0[0] + o0[1] * o0[1]) + (o0[2] * o0[2] + o0[3] * o0[3]) + (o1[0] * o1[0] + o1[1] * o1[1]) + (o1[2] * o1[2] + o1[3] * o1[3]);
;                         if (hb) { u32x4 w; w.x = pk2(o0[0], o0[1]); w.y = pk2(o0[2], o0[3]); w.z = pk2(o1[0], o1[1]); w.w = pk2(o1[2], o1[3]); *(u32x4*)(hb + off) = w; }
.LBB0_1896:
	s_or_b64 exec, exec, s[24:25]
	v_lshlrev_b32_e32 v140, 16, v136
	s_waitcnt lgkmcnt(0)
	v_and_b32_e32 v141, 0xffff0000, v136
	v_lshlrev_b32_e32 v136, 16, v137
	v_and_b32_e32 v137, 0xffff0000, v137
	v_lshlrev_b32_e32 v142, 16, v138
	v_and_b32_e32 v143, 0xffff0000, v138
	v_lshlrev_b32_e32 v138, 16, v139
	v_and_b32_e32 v139, 0xffff0000, v139
	s_mov_b32 s24, s52
	s_mov_b32 s25, s52
	v_lshl_add_u64 v[144:145], s[20:21], 0, v[164:165]
	v_pk_fma_f32 v[136:137], v[18:19], s[24:25], v[136:137]
	v_pk_fma_f32 v[140:141], v[16:17], s[52:53], v[140:141]
	v_pk_fma_f32 v[138:139], v[10:11], s[24:25], v[138:139]
	v_pk_fma_f32 v[142:143], v[8:9], s[52:53], v[142:143]
	s_and_b64 vcc, exec, s[48:49]
	v_lshl_add_u64 v[144:145], s[22:23], 1, v[144:145]
	s_cbranch_vccnz .LBB0_1898
	v_cvt_pk_bf16_f32 v146, v140, v141
	v_cvt_pk_bf16_f32 v147, v136, v137
	v_cvt_pk_bf16_f32 v148, v142, v143
	v_cvt_pk_bf16_f32 v149, v138, v139
	v_lshl_add_u64 v[150:151], v[144:145], 0, v[2:3]
	flat_store_dwordx4 v[150:151], v[146:149] sc1
.LBB0_1898:
	s_nop 1
	v_lshlrev_b32_e32 v146, 16, v132
	v_and_b32_e32 v147, 0xffff0000, v132
	v_lshlrev_b32_e32 v132, 16, v133
	v_and_b32_e32 v133, 0xffff0000, v133
	v_lshlrev_b32_e32 v148, 16, v134
	v_and_b32_e32 v149, 0xffff0000, v134
	v_lshlrev_b32_e32 v134, 16, v135
	v_and_b32_e32 v135, 0xffff0000, v135
	v_pk_fma_f32 v[132:133], v[14:15], s[24:25], v[132:133]
	v_pk_fma_f32 v[146:147], v[12:13], s[52:53], v[146:147]
	v_pk_fma_f32 v[134:135], v[6:7], s[24:25], v[134:135]
	s_and_b64 vcc, exec, s[48:49]
	v_pk_fma_f32 v[148:149], v[4:5], s[52:53], v[148:149]
	s_cbranch_vccnz .LBB0_1900
	v_cvt_pk_bf16_f32 v150, v146, v147
	v_cvt_pk_bf16_f32 v151, v132, v133
	v_cvt_pk_bf16_f32 v152, v148, v149
	v_cvt_pk_bf16_f32 v153, v134, v135
	v_lshl_add_u64 v[144:145], v[144:145], 0, v[2:3]
	flat_store_dwordx4 v[144:145], v[150:153] offset:256 sc1
